# NSA: PS quad shuffles via DPP quad_perm instead of ds_bpermute; softmax max butterflies via v_permlane16/32_swap
# speedup vs baseline: 1.0108x; 1.0108x over previous
.LBB0_445:
	v_subrev_u32_e32 v105, 31, v78
	v_lshrrev_b32_e32 v105, 4, v105
	v_bfe_u32 v84, v75, 4, 2
	v_add_u32_e32 v105, 1, v105
	v_cmp_lt_i32_e32 vcc, 30, v78
	v_lshlrev_b32_e32 v84, 3, v84
	v_or_b32_e32 v106, 1, v84
	v_cndmask_b32_e32 v108, 0, v105, vcc
	v_max_f32_e32 v105, v68, v68
	v_max_f32_e32 v105, 0xf149f2ca, v105
	v_cmp_lt_u32_e64 s[0:1], v84, v108
	v_max_f32_e32 v107, v69, v69
	v_max_f32_e32 v116, v65, v65
	v_writelane_b32 v254, s0, 42
	v_max_f32_e32 v119, v61, v61
	v_max_f32_e32 v120, v57, v57
	v_cndmask_b32_e64 v105, v92, v105, s[0:1]
	v_writelane_b32 v254, s1, 43
	v_max_f32_e32 v107, v105, v107
	v_cmp_lt_u32_e64 s[0:1], v106, v108
	v_or_b32_e32 v106, 2, v84
	v_max_f32_e32 v123, v14, v14
	v_writelane_b32 v254, s0, 44
	v_xor_b32_e32 v121, 16, v174
	v_xor_b32_e32 v122, 32, v174
	v_cndmask_b32_e64 v105, v105, v107, s[0:1]
	v_max_f32_e32 v107, v70, v70
	v_writelane_b32 v254, s1, 45
	v_max_f32_e32 v107, v105, v107
	v_cmp_lt_u32_e64 s[0:1], v106, v108
	v_or_b32_e32 v106, 3, v84
	s_nop 0
	v_writelane_b32 v254, s0, 46
	s_nop 1
	v_cndmask_b32_e64 v105, v105, v107, s[0:1]
	v_max_f32_e32 v107, v71, v71
	v_writelane_b32 v254, s1, 47
	v_max_f32_e32 v107, v105, v107
	v_cmp_lt_u32_e64 s[0:1], v106, v108
	s_nop 1
	v_writelane_b32 v254, s0, 48
	s_nop 1
	v_cndmask_b32_e64 v106, v105, v107, s[0:1]
	v_or_b32_e32 v105, 4, v84
	v_max_f32_e32 v107, v64, v64
	v_max_f32_e32 v107, v106, v107
	v_cmp_lt_u32_e64 s[52:53], v105, v108
	v_writelane_b32 v254, s1, 49
	s_nop 0
	v_cndmask_b32_e64 v106, v106, v107, s[52:53]
	v_or_b32_e32 v107, 5, v84
	v_max_f32_e32 v109, v106, v106
	v_max_f32_e32 v109, v109, v116
	v_cmp_lt_u32_e64 s[62:63], v107, v108
	v_or_b32_e32 v107, 6, v84
	v_max_f32_e32 v116, v66, v66
	v_cndmask_b32_e64 v106, v106, v109, s[62:63]
	v_max_f32_e32 v109, v106, v106
	v_max_f32_e32 v109, v109, v116
	v_cmp_lt_u32_e64 s[68:69], v107, v108
	v_or_b32_e32 v107, 7, v84
	v_max_f32_e32 v116, v67, v67
	v_cndmask_b32_e64 v106, v106, v109, s[68:69]
	v_max_f32_e32 v109, v106, v106
	v_max_f32_e32 v109, v109, v116
	v_cmp_lt_u32_e64 s[74:75], v107, v108
	v_max_f32_e32 v116, v60, v60
	s_nop 0
	v_cndmask_b32_e64 v107, v106, v109, s[74:75]
	v_or_b32_e32 v106, 32, v84
	v_max_f32_e32 v109, v107, v107
	v_max_f32_e32 v109, v109, v116
	v_cmp_lt_u32_e64 s[80:81], v106, v108
	s_nop 1
	v_cndmask_b32_e64 v107, v107, v109, s[80:81]
	v_or_b32_e32 v109, 33, v84
	v_max_f32_e32 v116, v107, v107
	v_max_f32_e32 v116, v116, v119
	v_cmp_lt_u32_e64 s[84:85], v109, v108
	v_or_b32_e32 v109, 34, v84
	v_max_f32_e32 v119, v62, v62
	v_cndmask_b32_e64 v107, v107, v116, s[84:85]
	v_max_f32_e32 v116, v107, v107
	v_max_f32_e32 v116, v116, v119
	v_cmp_lt_u32_e64 s[86:87], v109, v108
	v_or_b32_e32 v109, 35, v84
	v_max_f32_e32 v119, v63, v63
	v_cndmask_b32_e64 v107, v107, v116, s[86:87]
	v_max_f32_e32 v116, v107, v107
	v_max_f32_e32 v116, v116, v119
	v_cmp_lt_u32_e64 s[88:89], v109, v108
	v_max_f32_e32 v119, v56, v56
	s_nop 0
	v_cndmask_b32_e64 v109, v107, v116, s[88:89]
	v_or_b32_e32 v107, 36, v84
	v_max_f32_e32 v116, v109, v109
	v_max_f32_e32 v116, v116, v119
	v_cmp_lt_u32_e64 s[90:91], v107, v108
	s_nop 1
	v_cndmask_b32_e64 v109, v109, v116, s[90:91]
	v_or_b32_e32 v116, 37, v84
	v_max_f32_e32 v119, v109, v109
	v_max_f32_e32 v119, v119, v120
	v_cmp_lt_u32_e64 s[92:93], v116, v108
	v_or_b32_e32 v116, 38, v84
	v_max_f32_e32 v120, v58, v58
	v_cndmask_b32_e64 v109, v109, v119, s[92:93]
	v_max_f32_e32 v119, v109, v109
	v_max_f32_e32 v119, v119, v120
	v_cmp_lt_u32_e64 s[94:95], v116, v108
	v_or_b32_e32 v116, 39, v84
	v_max_f32_e32 v120, v59, v59
	v_cndmask_b32_e64 v109, v109, v119, s[94:95]
	v_max_f32_e32 v119, v109, v109
	v_max_f32_e32 v119, v119, v120
	v_cmp_lt_u32_e64 s[96:97], v116, v108
	v_or_b32_e32 v116, 64, v84
	v_max_f32_e32 v120, v52, v52
	v_cndmask_b32_e64 v109, v109, v119, s[96:97]
	v_max_f32_e32 v119, v109, v109
	v_max_f32_e32 v119, v119, v120
	v_cmp_lt_u32_e64 s[40:41], v116, v108
	v_or_b32_e32 v116, 0x41, v84
	v_max_f32_e32 v120, v53, v53
	v_cndmask_b32_e64 v109, v109, v119, s[40:41]
	v_max_f32_e32 v119, v109, v109
	v_max_f32_e32 v119, v119, v120
	v_cmp_lt_u32_e64 s[38:39], v116, v108
	v_or_b32_e32 v116, 0x42, v84
	v_max_f32_e32 v120, v54, v54
	v_cndmask_b32_e64 v109, v109, v119, s[38:39]
	v_max_f32_e32 v119, v109, v109
	v_max_f32_e32 v119, v119, v120
	v_cmp_lt_u32_e64 s[48:49], v116, v108
	v_or_b32_e32 v116, 0x43, v84
	v_max_f32_e32 v120, v55, v55
	v_cndmask_b32_e64 v109, v109, v119, s[48:49]
	v_max_f32_e32 v119, v109, v109
	v_max_f32_e32 v119, v119, v120
	v_cmp_lt_u32_e64 s[58:59], v116, v108
	v_or_b32_e32 v116, 0x44, v84
	v_max_f32_e32 v120, v36, v36
	v_cndmask_b32_e64 v109, v109, v119, s[58:59]
	v_max_f32_e32 v119, v109, v109
	v_max_f32_e32 v119, v119, v120
	v_cmp_lt_u32_e64 s[0:1], v116, v108
	v_or_b32_e32 v116, 0x45, v84
	v_max_f32_e32 v120, v37, v37
	v_writelane_b32 v254, s0, 50
	s_nop 1
	v_cndmask_b32_e64 v109, v109, v119, s[0:1]
	v_max_f32_e32 v119, v109, v109
	v_writelane_b32 v254, s1, 51
	v_max_f32_e32 v119, v119, v120
	v_cmp_lt_u32_e64 s[0:1], v116, v108
	v_or_b32_e32 v116, 0x46, v84
	v_max_f32_e32 v120, v38, v38
	v_writelane_b32 v254, s0, 52
	s_nop 1
	v_cndmask_b32_e64 v109, v109, v119, s[0:1]
	v_max_f32_e32 v119, v109, v109
	v_writelane_b32 v254, s1, 53
	v_max_f32_e32 v119, v119, v120
	v_cmp_lt_u32_e64 s[0:1], v116, v108
	v_or_b32_e32 v116, 0x47, v84
	v_max_f32_e32 v120, v39, v39
	v_writelane_b32 v254, s0, 54
	s_nop 1
	v_cndmask_b32_e64 v109, v109, v119, s[0:1]
	v_max_f32_e32 v119, v109, v109
	v_writelane_b32 v254, s1, 55
	v_max_f32_e32 v119, v119, v120
	v_cmp_lt_u32_e64 s[0:1], v116, v108
	v_or_b32_e32 v116, 0x60, v84
	v_max_f32_e32 v120, v24, v24
	v_writelane_b32 v254, s0, 56
	s_nop 1
	v_cndmask_b32_e64 v109, v109, v119, s[0:1]
	v_max_f32_e32 v119, v109, v109
	v_writelane_b32 v254, s1, 57
	v_max_f32_e32 v119, v119, v120
	v_cmp_lt_u32_e64 s[0:1], v116, v108
	v_or_b32_e32 v116, 0x61, v84
	v_max_f32_e32 v120, v25, v25
	v_writelane_b32 v254, s0, 58
	s_nop 1
	v_cndmask_b32_e64 v109, v109, v119, s[0:1]
	v_max_f32_e32 v119, v109, v109
	v_writelane_b32 v254, s1, 59
	v_max_f32_e32 v119, v119, v120
	v_cmp_lt_u32_e64 s[0:1], v116, v108
	v_or_b32_e32 v116, 0x62, v84
	v_max_f32_e32 v120, v26, v26
	v_writelane_b32 v254, s0, 60
	s_nop 1
	v_cndmask_b32_e64 v109, v109, v119, s[0:1]
	v_max_f32_e32 v119, v109, v109
	v_writelane_b32 v254, s1, 61
	v_max_f32_e32 v119, v119, v120
	v_cmp_lt_u32_e64 s[0:1], v116, v108
	v_or_b32_e32 v116, 0x63, v84
	v_max_f32_e32 v120, v27, v27
	v_writelane_b32 v254, s0, 62
	s_nop 1
	v_cndmask_b32_e64 v109, v109, v119, s[0:1]
	v_max_f32_e32 v119, v109, v109
	v_writelane_b32 v254, s1, 63
	v_max_f32_e32 v119, v119, v120
	v_cmp_lt_u32_e64 s[0:1], v116, v108
	v_or_b32_e32 v116, 0x64, v84
	v_max_f32_e32 v120, v16, v16
	v_writelane_b32 v255, s0, 0
	v_readlane_b32 s50, v254, 42
	v_readlane_b32 s51, v254, 43
	v_cndmask_b32_e64 v109, v109, v119, s[0:1]
	v_max_f32_e32 v119, v109, v109
	v_writelane_b32 v255, s1, 1
	v_max_f32_e32 v119, v119, v120
	v_cmp_lt_u32_e64 s[0:1], v116, v108
	v_or_b32_e32 v116, 0x65, v84
	v_max_f32_e32 v120, v17, v17
	v_writelane_b32 v255, s0, 2
	s_nop 1
	v_cndmask_b32_e64 v109, v109, v119, s[0:1]
	v_max_f32_e32 v119, v109, v109
	v_writelane_b32 v255, s1, 3
	v_max_f32_e32 v119, v119, v120
	v_cmp_lt_u32_e64 s[0:1], v116, v108
	v_or_b32_e32 v116, 0x66, v84
	v_max_f32_e32 v120, v18, v18
	v_writelane_b32 v255, s0, 4
	s_nop 1
	v_cndmask_b32_e64 v109, v109, v119, s[0:1]
	v_max_f32_e32 v119, v109, v109
	v_writelane_b32 v255, s1, 5
	v_max_f32_e32 v119, v119, v120
	v_cmp_lt_u32_e64 s[0:1], v116, v108
	v_or_b32_e32 v116, 0x67, v84
	v_max_f32_e32 v120, v19, v19
	v_writelane_b32 v255, s0, 6
	s_nop 1
	v_cndmask_b32_e64 v109, v109, v119, s[0:1]
	v_max_f32_e32 v119, v109, v109
	v_writelane_b32 v255, s1, 7
	v_max_f32_e32 v119, v119, v120
	v_cmp_lt_u32_e64 s[0:1], v116, v108
	v_or_b32_e32 v116, 0x80, v84
	v_max_f32_e32 v120, v40, v40
	v_writelane_b32 v255, s0, 8
	s_nop 1
	v_cndmask_b32_e64 v109, v109, v119, s[0:1]
	v_max_f32_e32 v119, v109, v109
	v_writelane_b32 v255, s1, 9
	v_max_f32_e32 v119, v119, v120
	v_cmp_lt_u32_e64 s[0:1], v116, v108
	v_or_b32_e32 v116, 0x81, v84
	v_max_f32_e32 v120, v41, v41
	v_writelane_b32 v255, s0, 10
	s_nop 1
	v_cndmask_b32_e64 v109, v109, v119, s[0:1]
	v_max_f32_e32 v119, v109, v109
	v_writelane_b32 v255, s1, 11
	v_max_f32_e32 v119, v119, v120
	v_cmp_lt_u32_e64 s[0:1], v116, v108
	v_or_b32_e32 v116, 0x82, v84
	v_max_f32_e32 v120, v42, v42
	v_writelane_b32 v255, s0, 12
	s_nop 1
	v_cndmask_b32_e64 v109, v109, v119, s[0:1]
	v_max_f32_e32 v119, v109, v109
	v_writelane_b32 v255, s1, 13
	v_max_f32_e32 v119, v119, v120
	v_cmp_lt_u32_e64 s[0:1], v116, v108
	v_or_b32_e32 v116, 0x83, v84
	v_max_f32_e32 v120, v43, v43
	v_writelane_b32 v255, s0, 14
	v_cmp_lt_u32_e64 s[56:57], v116, v108
	v_or_b32_e32 v116, 0x84, v84
	v_cndmask_b32_e64 v109, v109, v119, s[0:1]
	v_max_f32_e32 v119, v109, v109
	v_max_f32_e32 v119, v119, v120
	v_cndmask_b32_e64 v109, v109, v119, s[56:57]
	v_max_f32_e32 v119, v109, v109
	v_max_f32_e32 v120, v28, v28
	v_writelane_b32 v255, s1, 15
	v_max_f32_e32 v119, v119, v120
	v_cmp_lt_u32_e64 s[0:1], v116, v108
	v_or_b32_e32 v116, 0x85, v84
	v_max_f32_e32 v120, v29, v29
	v_writelane_b32 v255, s0, 16
	v_cmp_lt_u32_e64 s[64:65], v116, v108
	v_or_b32_e32 v116, 0x86, v84
	v_cndmask_b32_e64 v109, v109, v119, s[0:1]
	v_max_f32_e32 v119, v109, v109
	v_max_f32_e32 v119, v119, v120
	v_cndmask_b32_e64 v109, v109, v119, s[64:65]
	v_max_f32_e32 v119, v109, v109
	v_max_f32_e32 v120, v30, v30
	v_max_f32_e32 v119, v119, v120
	v_cmp_lt_u32_e64 s[60:61], v116, v108
	v_or_b32_e32 v116, 0x87, v84
	v_max_f32_e32 v120, v31, v31
	v_cndmask_b32_e64 v109, v109, v119, s[60:61]
	v_max_f32_e32 v119, v109, v109
	v_max_f32_e32 v119, v119, v120
	v_cmp_lt_u32_e64 s[70:71], v116, v108
	v_or_b32_e32 v116, 0xa0, v84
	v_max_f32_e32 v120, v20, v20
	v_cndmask_b32_e64 v109, v109, v119, s[70:71]
	v_max_f32_e32 v119, v109, v109
	v_max_f32_e32 v119, v119, v120
	v_cmp_lt_u32_e64 s[66:67], v116, v108
	v_or_b32_e32 v116, 0xa1, v84
	v_max_f32_e32 v120, v21, v21
	v_cndmask_b32_e64 v109, v109, v119, s[66:67]
	v_max_f32_e32 v119, v109, v109
	v_max_f32_e32 v119, v119, v120
	v_cmp_lt_u32_e64 s[78:79], v116, v108
	v_or_b32_e32 v116, 0xa2, v84
	v_max_f32_e32 v120, v22, v22
	v_cndmask_b32_e64 v109, v109, v119, s[78:79]
	v_max_f32_e32 v119, v109, v109
	v_max_f32_e32 v119, v119, v120
	v_cmp_lt_u32_e64 s[72:73], v116, v108
	v_or_b32_e32 v116, 0xa3, v84
	v_max_f32_e32 v120, v23, v23
	v_cndmask_b32_e64 v109, v109, v119, s[72:73]
	v_max_f32_e32 v119, v109, v109
	v_max_f32_e32 v119, v119, v120
	v_cmp_lt_u32_e64 s[82:83], v116, v108
	v_or_b32_e32 v116, 0xa4, v84
	v_max_f32_e32 v120, v12, v12
	v_cndmask_b32_e64 v109, v109, v119, s[82:83]
	v_max_f32_e32 v119, v109, v109
	v_max_f32_e32 v119, v119, v120
	v_cmp_lt_u32_e64 s[76:77], v116, v108
	v_max_f32_e32 v120, v13, v13
	v_writelane_b32 v255, s1, 17
	v_cndmask_b32_e64 v109, v109, v119, s[76:77]
	v_or_b32_e32 v119, 0xa5, v84
	v_max_f32_e32 v116, v109, v109
	v_max_f32_e32 v120, v116, v120
	v_cmp_lt_u32_e64 s[26:27], v119, v108
	v_or_b32_e32 v119, 0xa6, v84
	v_cmp_lt_u32_e64 s[36:37], v119, v108
	v_cndmask_b32_e64 v109, v109, v120, s[26:27]
	v_max_f32_e32 v120, v109, v109
	v_max_f32_e32 v120, v120, v123
	v_cndmask_b32_e64 v109, v109, v120, s[36:37]
	v_or_b32_e32 v119, 0xa7, v84
	v_max_f32_e32 v120, v109, v109
	v_max_f32_e32 v123, v15, v15
	v_max_f32_e32 v120, v120, v123
	v_cmp_lt_u32_e64 s[22:23], v119, v108
	v_or_b32_e32 v119, 0xc0, v84
	v_max_f32_e32 v123, v48, v48
	v_cndmask_b32_e64 v109, v109, v120, s[22:23]
	v_max_f32_e32 v120, v109, v109
	v_max_f32_e32 v120, v120, v123
	v_cmp_lt_u32_e64 s[34:35], v119, v108
	v_or_b32_e32 v119, 0xc1, v84
	v_max_f32_e32 v123, v49, v49
	v_cndmask_b32_e64 v109, v109, v120, s[34:35]
	v_max_f32_e32 v120, v109, v109
	v_max_f32_e32 v120, v120, v123
	v_cmp_lt_u32_e64 s[18:19], v119, v108
	v_or_b32_e32 v119, 0xc2, v84
	v_max_f32_e32 v123, v50, v50
	v_cndmask_b32_e64 v109, v109, v120, s[18:19]
	v_max_f32_e32 v120, v109, v109
	v_max_f32_e32 v120, v120, v123
	v_cmp_lt_u32_e64 s[30:31], v119, v108
	v_or_b32_e32 v119, 0xc3, v84
	v_max_f32_e32 v123, v51, v51
	v_cndmask_b32_e64 v109, v109, v120, s[30:31]
	v_max_f32_e32 v120, v109, v109
	v_max_f32_e32 v120, v120, v123
	v_cmp_lt_u32_e64 s[14:15], v119, v108
	v_or_b32_e32 v119, 0xc4, v84
	v_max_f32_e32 v123, v44, v44
	v_cndmask_b32_e64 v109, v109, v120, s[14:15]
	v_max_f32_e32 v120, v109, v109
	v_max_f32_e32 v120, v120, v123
	v_cmp_lt_u32_e64 s[28:29], v119, v108
	v_or_b32_e32 v119, 0xc5, v84
	v_max_f32_e32 v123, v45, v45
	v_cndmask_b32_e64 v109, v109, v120, s[28:29]
	v_max_f32_e32 v120, v109, v109
	v_max_f32_e32 v120, v120, v123
	v_cmp_lt_u32_e64 s[10:11], v119, v108
	v_or_b32_e32 v119, 0xc6, v84
	v_max_f32_e32 v123, v46, v46
	v_cndmask_b32_e64 v109, v109, v120, s[10:11]
	v_max_f32_e32 v120, v109, v109
	v_max_f32_e32 v120, v120, v123
	v_cmp_lt_u32_e64 s[24:25], v119, v108
	v_or_b32_e32 v119, 0xc7, v84
	v_max_f32_e32 v123, v47, v47
	v_cndmask_b32_e64 v109, v109, v120, s[24:25]
	v_max_f32_e32 v120, v109, v109
	v_max_f32_e32 v120, v120, v123
	v_cmp_lt_u32_e64 s[6:7], v119, v108
	v_or_b32_e32 v119, 0xe0, v84
	v_max_f32_e32 v123, v32, v32
	v_cndmask_b32_e64 v109, v109, v120, s[6:7]
	v_max_f32_e32 v120, v109, v109
	v_max_f32_e32 v120, v120, v123
	v_cmp_lt_u32_e64 s[20:21], v119, v108
	v_or_b32_e32 v119, 0xe1, v84
	v_max_f32_e32 v123, v33, v33
	v_cndmask_b32_e64 v109, v109, v120, s[20:21]
	v_max_f32_e32 v120, v109, v109
	v_max_f32_e32 v120, v120, v123
	v_cmp_lt_u32_e64 s[4:5], v119, v108
	v_or_b32_e32 v119, 0xe2, v84
	v_max_f32_e32 v123, v34, v34
	v_cndmask_b32_e64 v109, v109, v120, s[4:5]
	v_max_f32_e32 v120, v109, v109
	v_max_f32_e32 v120, v120, v123
	v_cmp_lt_u32_e64 s[16:17], v119, v108
	v_or_b32_e32 v119, 0xe3, v84
	v_max_f32_e32 v123, v35, v35
	v_cndmask_b32_e64 v109, v109, v120, s[16:17]
	v_max_f32_e32 v120, v109, v109
	v_max_f32_e32 v120, v120, v123
	v_cmp_lt_u32_e64 s[2:3], v119, v108
	v_or_b32_e32 v119, 0xe4, v84
	v_max_f32_e32 v123, v8, v8
	v_cndmask_b32_e64 v109, v109, v120, s[2:3]
	v_max_f32_e32 v120, v109, v109
	v_max_f32_e32 v120, v120, v123
	v_cmp_lt_u32_e64 s[12:13], v119, v108
	v_or_b32_e32 v119, 0xe5, v84
	v_max_f32_e32 v123, v9, v9
	v_cndmask_b32_e64 v109, v109, v120, s[12:13]
	v_max_f32_e32 v120, v109, v109
	v_max_f32_e32 v120, v120, v123
	v_cmp_lt_u32_e64 s[0:1], v119, v108
	v_and_b32_e32 v116, 64, v174
	v_or_b32_e32 v119, 0xe6, v84
	v_cndmask_b32_e64 v109, v109, v120, s[0:1]
	v_max_f32_e32 v120, v109, v109
	v_max_f32_e32 v123, v10, v10
	v_add_u32_e32 v116, 64, v116
	v_max_f32_e32 v120, v120, v123
	v_cmp_lt_u32_e64 s[8:9], v119, v108
	v_cmp_lt_i32_e32 vcc, v121, v116
	v_or_b32_e32 v119, 0xe7, v84
	v_cndmask_b32_e64 v109, v109, v120, s[8:9]
	v_cndmask_b32_e32 v121, v174, v121, vcc
	v_cmp_lt_i32_e32 vcc, v122, v116
	v_max_f32_e32 v120, v109, v109
	v_max_f32_e32 v123, v11, v11
	v_cndmask_b32_e32 v122, v174, v122, vcc
	v_max_f32_e32 v120, v120, v123
	v_cmp_lt_u32_e32 vcc, v119, v108
	v_lshlrev_b32_e32 v108, 2, v121
	s_nop 0
	v_cndmask_b32_e32 v109, v109, v120, vcc
	ds_bpermute_b32 v119, v108, v109
	v_max_f32_e32 v109, v109, v109
	s_waitcnt lgkmcnt(0)
	v_max_f32_e32 v119, v119, v119
	v_max_f32_e32 v119, v109, v119
	v_lshlrev_b32_e32 v109, 2, v122
	ds_bpermute_b32 v120, v109, v119
	s_waitcnt lgkmcnt(0)
	v_max_f32_e32 v120, v120, v120
	v_max_f32_e32 v142, v119, v120
	v_sub_f32_e32 v64, v64, v142
	v_exp_f32_e32 v64, v64
	v_sub_f32_e32 v60, v60, v142
	v_sub_f32_e32 v52, v52, v142
	v_exp_f32_e32 v60, v60
	v_exp_f32_e32 v52, v52
	v_cndmask_b32_e64 v138, 0, v64, s[52:53]
	v_sub_f32_e32 v64, v65, v142
	v_exp_f32_e32 v64, v64
	v_cndmask_b32_e64 v134, 0, v60, s[80:81]
	v_sub_f32_e32 v60, v61, v142
	v_cndmask_b32_e64 v65, 0, v52, s[40:41]
	v_sub_f32_e32 v52, v53, v142
	v_exp_f32_e32 v60, v60
	v_exp_f32_e32 v52, v52
	v_cndmask_b32_e64 v137, 0, v64, s[62:63]
	v_sub_f32_e32 v64, v66, v142
	v_sub_f32_e32 v36, v36, v142
	v_exp_f32_e32 v64, v64
	v_exp_f32_e32 v36, v36
	v_sub_f32_e32 v37, v37, v142
	v_cndmask_b32_e64 v133, 0, v60, s[84:85]
	v_sub_f32_e32 v60, v62, v142
	v_cndmask_b32_e64 v62, 0, v52, s[38:39]
	v_exp_f32_e32 v37, v37
	v_readlane_b32 s38, v254, 50
	v_sub_f32_e32 v68, v68, v142
	v_readlane_b32 s39, v254, 51
	v_exp_f32_e32 v68, v68
	v_cndmask_b32_e64 v136, 0, v64, s[68:69]
	v_sub_f32_e32 v64, v67, v142
	v_cndmask_b32_e64 v67, 0, v36, s[38:39]
	v_readlane_b32 s38, v254, 52
	v_readlane_b32 s39, v254, 53
	v_cndmask_b32_e64 v143, 0, v68, s[50:51]
	v_sub_f32_e32 v68, v69, v142
	v_cndmask_b32_e64 v127, 0, v37, s[38:39]
	v_sub_f32_e32 v37, v38, v142
	v_exp_f32_e32 v37, v37
	v_sub_f32_e32 v38, v39, v142
	v_exp_f32_e32 v68, v68
	v_exp_f32_e32 v38, v38
	v_readlane_b32 s38, v254, 54
	v_readlane_b32 s39, v254, 55
	v_sub_f32_e32 v24, v24, v142
	v_readlane_b32 s50, v254, 44
	v_cndmask_b32_e64 v125, 0, v37, s[38:39]
	v_readlane_b32 s38, v254, 56
	v_exp_f32_e32 v24, v24
	v_readlane_b32 s51, v254, 45
	v_readlane_b32 s39, v254, 57
	v_sub_f32_e32 v25, v25, v142
	v_cndmask_b32_e64 v141, 0, v68, s[50:51]
	v_sub_f32_e32 v68, v70, v142
	v_cndmask_b32_e64 v70, 0, v38, s[38:39]
	v_exp_f32_e32 v25, v25
	v_readlane_b32 s38, v254, 58
	v_readlane_b32 s39, v254, 59
	v_exp_f32_e32 v68, v68
	v_sub_f32_e32 v56, v56, v142
	v_cndmask_b32_e64 v123, 0, v24, s[38:39]
	v_readlane_b32 s38, v254, 60
	v_readlane_b32 s39, v254, 61
	v_readlane_b32 s50, v254, 46
	v_exp_f32_e32 v56, v56
	v_cndmask_b32_e64 v122, 0, v25, s[38:39]
	v_sub_f32_e32 v25, v26, v142
	v_exp_f32_e32 v25, v25
	v_readlane_b32 s51, v254, 47
	v_sub_f32_e32 v26, v27, v142
	v_exp_f32_e32 v26, v26
	v_cndmask_b32_e64 v140, 0, v68, s[50:51]
	v_sub_f32_e32 v68, v71, v142
	v_readlane_b32 s38, v254, 62
	v_exp_f32_e32 v68, v68
	v_readlane_b32 s39, v254, 63
	v_sub_f32_e32 v16, v16, v142
	v_cndmask_b32_e64 v130, 0, v56, s[90:91]
	v_sub_f32_e32 v56, v57, v142
	v_cndmask_b32_e64 v121, 0, v25, s[38:39]
	v_readlane_b32 s38, v255, 0
	v_exp_f32_e32 v16, v16
	v_readlane_b32 s50, v254, 48
	v_exp_f32_e32 v56, v56
	v_add_f32_e32 v52, 0, v143
	v_readlane_b32 s39, v255, 1
	v_sub_f32_e32 v17, v17, v142
	v_readlane_b32 s51, v254, 49
	v_exp_f32_e32 v60, v60
	v_add_f32_e32 v52, v141, v52
	v_cndmask_b32_e64 v120, 0, v26, s[38:39]
	v_exp_f32_e32 v17, v17
	v_readlane_b32 s38, v255, 2
	v_cndmask_b32_e64 v139, 0, v68, s[50:51]
	v_exp_f32_e32 v64, v64
	v_add_f32_e32 v52, v140, v52
	v_readlane_b32 s39, v255, 3
	v_add_f32_e32 v52, v139, v52
	v_cndmask_b32_e64 v129, 0, v56, s[92:93]
	v_cndmask_b32_e64 v119, 0, v16, s[38:39]
	v_readlane_b32 s38, v255, 4
	v_sub_f32_e32 v56, v58, v142
	v_add_f32_e32 v52, v138, v52
	v_readlane_b32 s39, v255, 5
	v_cndmask_b32_e64 v132, 0, v60, s[86:87]
	v_sub_f32_e32 v60, v63, v142
	v_exp_f32_e32 v56, v56
	v_add_f32_e32 v52, v137, v52
	v_cndmask_b32_e64 v69, 0, v17, s[38:39]
	v_sub_f32_e32 v17, v18, v142
	v_cndmask_b32_e64 v135, 0, v64, s[74:75]
	v_exp_f32_e32 v60, v60
	v_add_f32_e32 v52, v136, v52
	v_exp_f32_e32 v17, v17
	v_add_f32_e32 v52, v135, v52
	v_sub_f32_e32 v18, v19, v142
	v_add_f32_e32 v52, v134, v52
	v_exp_f32_e32 v18, v18
	v_readlane_b32 s38, v255, 6
	v_cndmask_b32_e64 v128, 0, v56, s[94:95]
	v_sub_f32_e32 v56, v59, v142
	v_add_f32_e32 v52, v133, v52
	v_readlane_b32 s39, v255, 7
	v_cndmask_b32_e64 v131, 0, v60, s[88:89]
	v_exp_f32_e32 v56, v56
	v_add_f32_e32 v52, v132, v52
	v_cndmask_b32_e64 v68, 0, v17, s[38:39]
	v_readlane_b32 s38, v255, 8
	v_sub_f32_e32 v17, v40, v142
	v_add_f32_e32 v52, v131, v52
	v_readlane_b32 s39, v255, 9
	v_exp_f32_e32 v17, v17
	v_add_f32_e32 v52, v130, v52
	v_sub_f32_e32 v53, v54, v142
	v_cndmask_b32_e64 v66, 0, v18, s[38:39]
	v_sub_f32_e32 v18, v41, v142
	v_add_f32_e32 v52, v129, v52
	v_exp_f32_e32 v53, v53
	v_sub_f32_e32 v54, v55, v142
	v_exp_f32_e32 v18, v18
	v_readlane_b32 s38, v255, 10
	v_cndmask_b32_e64 v124, 0, v56, s[96:97]
	v_add_f32_e32 v52, v128, v52
	v_exp_f32_e32 v54, v54
	v_readlane_b32 s39, v255, 11
	v_add_f32_e32 v52, v124, v52
	v_add_f32_e32 v52, v65, v52
	v_cndmask_b32_e64 v64, 0, v17, s[38:39]
	v_readlane_b32 s38, v255, 12
	v_readlane_b32 s39, v255, 13
	v_sub_f32_e32 v17, v42, v142
	v_add_f32_e32 v52, v62, v52
	v_cndmask_b32_e64 v126, 0, v53, s[48:49]
	v_cndmask_b32_e64 v63, 0, v18, s[38:39]
	v_exp_f32_e32 v17, v17
	v_sub_f32_e32 v18, v43, v142
	v_sub_f32_e32 v13, v13, v142
	v_add_f32_e32 v52, v126, v52
	v_cndmask_b32_e64 v71, 0, v54, s[58:59]
	v_exp_f32_e32 v18, v18
	v_exp_f32_e32 v13, v13
	v_add_f32_e32 v52, v71, v52
	v_readlane_b32 s38, v255, 14
	v_add_f32_e32 v36, v67, v52
	v_readlane_b32 s39, v255, 15
	v_add_f32_e32 v36, v127, v36
	v_add_f32_e32 v36, v125, v36
	v_cndmask_b32_e64 v61, 0, v17, s[38:39]
	v_sub_f32_e32 v17, v28, v142
	v_cndmask_b32_e64 v60, 0, v18, s[56:57]
	v_exp_f32_e32 v17, v17
	v_sub_f32_e32 v18, v29, v142
	v_cndmask_b32_e64 v41, 0, v13, s[26:27]
	v_sub_f32_e32 v13, v14, v142
	v_add_f32_e32 v36, v70, v36
	v_exp_f32_e32 v18, v18
	v_exp_f32_e32 v13, v13
	v_sub_f32_e32 v14, v15, v142
	v_add_f32_e32 v24, v123, v36
	v_readlane_b32 s38, v255, 16
	v_exp_f32_e32 v14, v14
	v_add_f32_e32 v24, v122, v24
	v_readlane_b32 s39, v255, 17
	v_add_f32_e32 v24, v121, v24
	v_add_f32_e32 v24, v120, v24
	v_cndmask_b32_e64 v59, 0, v17, s[38:39]
	v_sub_f32_e32 v17, v30, v142
	v_cndmask_b32_e64 v58, 0, v18, s[64:65]
	v_exp_f32_e32 v17, v17
	v_sub_f32_e32 v18, v31, v142
	v_cndmask_b32_e64 v40, 0, v13, s[36:37]
	v_sub_f32_e32 v13, v48, v142
	v_add_f32_e32 v16, v119, v24
	v_exp_f32_e32 v18, v18
	v_cndmask_b32_e64 v39, 0, v14, s[22:23]
	v_exp_f32_e32 v13, v13
	v_sub_f32_e32 v14, v49, v142
	v_add_f32_e32 v16, v69, v16
	v_exp_f32_e32 v14, v14
	v_add_f32_e32 v16, v68, v16
	v_add_f32_e32 v16, v66, v16
	v_cndmask_b32_e64 v57, 0, v17, s[60:61]
	v_sub_f32_e32 v17, v20, v142
	v_add_f32_e32 v16, v64, v16
	v_cndmask_b32_e64 v56, 0, v18, s[70:71]
	v_exp_f32_e32 v17, v17
	v_sub_f32_e32 v18, v21, v142
	v_cndmask_b32_e64 v38, 0, v13, s[34:35]
	v_sub_f32_e32 v13, v50, v142
	v_add_f32_e32 v16, v63, v16
	v_exp_f32_e32 v18, v18
	v_cndmask_b32_e64 v30, 0, v14, s[18:19]
	v_exp_f32_e32 v13, v13
	v_sub_f32_e32 v14, v51, v142
	v_add_f32_e32 v16, v61, v16
	v_exp_f32_e32 v14, v14
	v_add_f32_e32 v16, v60, v16
	v_add_f32_e32 v16, v59, v16
	v_cndmask_b32_e64 v55, 0, v17, s[66:67]
	v_sub_f32_e32 v17, v22, v142
	v_add_f32_e32 v16, v58, v16
	v_cndmask_b32_e64 v54, 0, v18, s[78:79]
	v_exp_f32_e32 v17, v17
	v_sub_f32_e32 v18, v23, v142
	v_cndmask_b32_e64 v29, 0, v13, s[30:31]
	v_sub_f32_e32 v13, v44, v142
	v_add_f32_e32 v16, v57, v16
	v_exp_f32_e32 v18, v18
	v_sub_f32_e32 v12, v12, v142
	v_cndmask_b32_e64 v27, 0, v14, s[14:15]
	v_exp_f32_e32 v13, v13
	v_sub_f32_e32 v14, v45, v142
	v_add_f32_e32 v16, v56, v16
	v_exp_f32_e32 v12, v12
	v_exp_f32_e32 v14, v14
	v_add_f32_e32 v16, v55, v16
	v_add_f32_e32 v16, v54, v16
	v_cndmask_b32_e64 v53, 0, v17, s[72:73]
	v_add_f32_e32 v16, v53, v16
	v_cndmask_b32_e64 v52, 0, v18, s[82:83]
	v_cndmask_b32_e64 v26, 0, v13, s[28:29]
	v_sub_f32_e32 v13, v46, v142
	v_add_f32_e32 v16, v52, v16
	v_cndmask_b32_e64 v43, 0, v12, s[76:77]
	v_cndmask_b32_e64 v24, 0, v14, s[10:11]
	v_exp_f32_e32 v13, v13
	v_sub_f32_e32 v14, v47, v142
	v_add_f32_e32 v12, v43, v16
	v_exp_f32_e32 v14, v14
	v_add_f32_e32 v12, v41, v12
	v_add_f32_e32 v12, v40, v12
	v_add_f32_e32 v12, v39, v12
	v_cndmask_b32_e64 v22, 0, v13, s[24:25]
	v_sub_f32_e32 v13, v32, v142
	v_add_f32_e32 v12, v38, v12
	v_cndmask_b32_e64 v21, 0, v14, s[6:7]
	v_exp_f32_e32 v13, v13
	v_sub_f32_e32 v14, v33, v142
	v_add_f32_e32 v12, v30, v12
	v_exp_f32_e32 v14, v14
	v_add_f32_e32 v12, v29, v12
	v_add_f32_e32 v12, v27, v12
	v_add_f32_e32 v12, v26, v12
	v_cndmask_b32_e64 v20, 0, v13, s[20:21]
	v_sub_f32_e32 v13, v34, v142
	v_add_f32_e32 v12, v24, v12
	v_cndmask_b32_e64 v19, 0, v14, s[4:5]
	v_exp_f32_e32 v13, v13
	v_sub_f32_e32 v14, v35, v142
	v_add_f32_e32 v12, v22, v12
	v_exp_f32_e32 v14, v14
	v_sub_f32_e32 v8, v8, v142
	v_add_f32_e32 v12, v21, v12
	v_exp_f32_e32 v8, v8
	v_sub_f32_e32 v9, v9, v142
	v_add_f32_e32 v12, v20, v12
	v_exp_f32_e32 v9, v9
	v_add_f32_e32 v12, v19, v12
	v_cndmask_b32_e64 v17, 0, v13, s[16:17]
	v_add_f32_e32 v12, v17, v12
	v_cndmask_b32_e64 v14, 0, v14, s[2:3]
	v_add_f32_e32 v12, v14, v12
	v_cndmask_b32_e64 v13, 0, v8, s[12:13]
	v_add_f32_e32 v8, v13, v12
	v_cndmask_b32_e64 v12, 0, v9, s[0:1]
	v_sub_f32_e32 v9, v10, v142
	v_exp_f32_e32 v9, v9
	v_sub_f32_e32 v10, v11, v142
	v_exp_f32_e32 v10, v10
	v_add_f32_e32 v8, v12, v8
	v_cndmask_b32_e64 v9, 0, v9, s[8:9]
	v_add_f32_e32 v11, v9, v8
	v_cndmask_b32_e32 v8, 0, v10, vcc
	v_add_f32_e32 v10, v8, v11
	ds_bpermute_b32 v11, v108, v10
	v_readlane_b32 s15, v254, 38
	v_readlane_b32 s65, v254, 31
	s_waitcnt lgkmcnt(0)
	v_add_f32_e32 v10, v10, v11
	ds_bpermute_b32 v11, v109, v10
	s_waitcnt lgkmcnt(0)
	v_add_f32_e32 v10, v10, v11
	v_div_scale_f32 v11, s[0:1], v10, v10, 1.0
	v_rcp_f32_e32 v15, v11
	s_nop 0
	v_fma_f32 v16, -v11, v15, 1.0
	v_fmac_f32_e32 v15, v16, v15
	v_div_scale_f32 v16, vcc, 1.0, v10, 1.0
	v_mul_f32_e32 v18, v16, v15
	v_fma_f32 v23, -v11, v18, v16
	v_fmac_f32_e32 v18, v23, v15
	v_fma_f32 v11, -v11, v18, v16
	v_div_fmas_f32 v11, v11, v15, v18
	v_div_fixup_f32 v11, v11, v10, 1.0
	v_cmp_lt_f32_e32 vcc, 0, v10
	v_xor_b32_e32 v10, 1, v174
	v_xor_b32_e32 v15, 2, v174
	v_cndmask_b32_e32 v11, 0, v11, vcc
	v_cmp_lt_i32_e32 vcc, v10, v116
	v_lshlrev_b32_e32 v23, 2, v84
	s_nop 0
	v_cndmask_b32_e32 v10, v174, v10, vcc
	v_lshlrev_b32_e32 v36, 2, v10
	v_mul_f32_e32 v10, v143, v11
	s_nop 1
	v_mov_b32_dpp v16, v10 quad_perm:[1,0,3,2] row_mask:0xf bank_mask:0xf
	v_cmp_lt_i32_e32 vcc, v15, v116
	v_fmac_f32_e32 v16, v143, v11
	v_cndmask_b32_e32 v15, v174, v15, vcc
	v_lshlrev_b32_e32 v37, 2, v15
	s_nop 1
	v_mov_b32_dpp v18, v16 quad_perm:[2,3,0,1] row_mask:0xf bank_mask:0xf
	v_or_b32_e32 v15, s15, v88
	v_lshlrev_b32_e32 v15, 10, v15
	v_cmp_eq_u32_e32 vcc, 0, v118
	v_add3_u32 v15, s65, v15, v23
	s_and_saveexec_b64 s[0:1], vcc
	s_cbranch_execz .LBB0_447
	v_add_f32_e32 v16, v16, v18
	ds_write_b32 v15, v16
.LBB0_447:
	s_or_b64 exec, exec, s[0:1]
	v_mul_f32_e32 v16, v141, v11
	s_nop 1
	v_mov_b32_dpp v18, v16 quad_perm:[1,0,3,2] row_mask:0xf bank_mask:0xf
	v_fmac_f32_e32 v18, v141, v11
	s_nop 1
	v_mov_b32_dpp v23, v18 quad_perm:[2,3,0,1] row_mask:0xf bank_mask:0xf
	s_and_saveexec_b64 s[0:1], vcc
	s_cbranch_execz .LBB0_449
	v_add_f32_e32 v18, v18, v23
	ds_write_b32 v15, v18 offset:4
.LBB0_449:
	s_or_b64 exec, exec, s[0:1]
	v_mul_f32_e32 v18, v140, v11
	s_nop 1
	v_mov_b32_dpp v23, v18 quad_perm:[1,0,3,2] row_mask:0xf bank_mask:0xf
	v_fmac_f32_e32 v23, v140, v11
	s_nop 1
	v_mov_b32_dpp v25, v23 quad_perm:[2,3,0,1] row_mask:0xf bank_mask:0xf
	s_mov_b64 s[0:1], exec
	v_readlane_b32 s88, v254, 12
	v_readlane_b32 s90, v254, 14
	v_readlane_b32 s92, v254, 16
	v_readlane_b32 s94, v254, 19
	v_readlane_b32 s74, v254, 23
	v_readlane_b32 s66, v254, 27
	v_readlane_b32 s4, v254, 40
	v_readlane_b32 s6, v254, 36
	s_and_b64 s[2:3], s[0:1], vcc
	v_readlane_b32 s86, v254, 10
	v_readlane_b32 s89, v254, 13
	v_readlane_b32 s91, v254, 15
	v_readlane_b32 s93, v254, 17
	v_readlane_b32 s85, v254, 18
	v_readlane_b32 s95, v254, 20
	v_readlane_b32 s71, v254, 21
	v_readlane_b32 s72, v254, 22
	v_readlane_b32 s75, v254, 24
	v_readlane_b32 s96, v254, 25
	v_readlane_b32 s97, v254, 26
	v_readlane_b32 s67, v254, 28
	v_readlane_b32 s14, v254, 39
	v_readlane_b32 s5, v254, 41
	v_readlane_b32 s7, v254, 37
	v_readlane_b32 s87, v254, 11
	s_mov_b64 exec, s[2:3]
	s_cbranch_execz .LBB0_451
	v_add_f32_e32 v23, v23, v25
	ds_write_b32 v15, v23 offset:8
.LBB0_451:
	s_or_b64 exec, exec, s[0:1]
	v_mul_f32_e32 v23, v139, v11
	s_nop 1
	v_mov_b32_dpp v25, v23 quad_perm:[1,0,3,2] row_mask:0xf bank_mask:0xf
	v_fmac_f32_e32 v25, v139, v11
	s_nop 1
	v_mov_b32_dpp v28, v25 quad_perm:[2,3,0,1] row_mask:0xf bank_mask:0xf
	s_and_saveexec_b64 s[0:1], vcc
	s_cbranch_execz .LBB0_453
	v_add_f32_e32 v25, v25, v28
	ds_write_b32 v15, v25 offset:12
.LBB0_453:
	s_or_b64 exec, exec, s[0:1]
	v_mul_f32_e32 v25, v138, v11
	s_nop 1
	v_mov_b32_dpp v28, v25 quad_perm:[1,0,3,2] row_mask:0xf bank_mask:0xf
	v_fmac_f32_e32 v28, v138, v11
	s_nop 1
	v_mov_b32_dpp v31, v28 quad_perm:[2,3,0,1] row_mask:0xf bank_mask:0xf
	s_and_saveexec_b64 s[0:1], vcc
	s_cbranch_execz .LBB0_455
	v_add_f32_e32 v28, v28, v31
	ds_write_b32 v15, v28 offset:16
.LBB0_455:
	s_or_b64 exec, exec, s[0:1]
	v_mul_f32_e32 v28, v137, v11
	s_nop 1
	v_mov_b32_dpp v31, v28 quad_perm:[1,0,3,2] row_mask:0xf bank_mask:0xf
	v_fmac_f32_e32 v31, v137, v11
	s_nop 1
	v_mov_b32_dpp v32, v31 quad_perm:[2,3,0,1] row_mask:0xf bank_mask:0xf
	s_and_saveexec_b64 s[0:1], vcc
	s_cbranch_execz .LBB0_457
	v_add_f32_e32 v31, v31, v32
	ds_write_b32 v15, v31 offset:20
.LBB0_457:
	s_or_b64 exec, exec, s[0:1]
	v_mul_f32_e32 v31, v136, v11
	s_nop 1
	v_mov_b32_dpp v32, v31 quad_perm:[1,0,3,2] row_mask:0xf bank_mask:0xf
	v_fmac_f32_e32 v32, v136, v11
	s_nop 1
	v_mov_b32_dpp v33, v32 quad_perm:[2,3,0,1] row_mask:0xf bank_mask:0xf
	s_and_saveexec_b64 s[0:1], vcc
	s_cbranch_execz .LBB0_459
	v_add_f32_e32 v32, v32, v33
	ds_write_b32 v15, v32 offset:24
.LBB0_459:
	s_or_b64 exec, exec, s[0:1]
	v_mul_f32_e32 v33, v135, v11
	s_nop 1
	v_mov_b32_dpp v32, v33 quad_perm:[1,0,3,2] row_mask:0xf bank_mask:0xf
	v_fmac_f32_e32 v32, v135, v11
	s_nop 1
	v_mov_b32_dpp v34, v32 quad_perm:[2,3,0,1] row_mask:0xf bank_mask:0xf
	s_and_saveexec_b64 s[0:1], vcc
	s_cbranch_execz .LBB0_461
	v_add_f32_e32 v32, v32, v34
	ds_write_b32 v15, v32 offset:28
.LBB0_461:
	s_or_b64 exec, exec, s[0:1]
	v_mul_f32_e32 v32, v134, v11
	s_nop 1
	v_mov_b32_dpp v34, v32 quad_perm:[1,0,3,2] row_mask:0xf bank_mask:0xf
	v_fmac_f32_e32 v34, v134, v11
	s_nop 1
	v_mov_b32_dpp v35, v34 quad_perm:[2,3,0,1] row_mask:0xf bank_mask:0xf
	s_and_saveexec_b64 s[0:1], vcc
	s_cbranch_execz .LBB0_463
	v_add_f32_e32 v34, v34, v35
	ds_write_b32 v15, v34 offset:128
.LBB0_463:
	s_or_b64 exec, exec, s[0:1]
	v_mul_f32_e32 v34, v133, v11
	s_nop 1
	v_mov_b32_dpp v35, v34 quad_perm:[1,0,3,2] row_mask:0xf bank_mask:0xf
	v_fmac_f32_e32 v35, v133, v11
	s_nop 1
	v_mov_b32_dpp v42, v35 quad_perm:[2,3,0,1] row_mask:0xf bank_mask:0xf
	s_and_saveexec_b64 s[0:1], vcc
	s_cbranch_execz .LBB0_465
	v_add_f32_e32 v35, v35, v42
	ds_write_b32 v15, v35 offset:132
.LBB0_465:
	s_or_b64 exec, exec, s[0:1]
	v_mul_f32_e32 v35, v132, v11
	s_nop 1
	v_mov_b32_dpp v42, v35 quad_perm:[1,0,3,2] row_mask:0xf bank_mask:0xf
	v_fmac_f32_e32 v42, v132, v11
	s_nop 1
	v_mov_b32_dpp v44, v42 quad_perm:[2,3,0,1] row_mask:0xf bank_mask:0xf
	s_and_saveexec_b64 s[0:1], vcc
	s_cbranch_execz .LBB0_467
	v_add_f32_e32 v42, v42, v44
	ds_write_b32 v15, v42 offset:136
.LBB0_467:
	s_or_b64 exec, exec, s[0:1]
	v_mul_f32_e32 v42, v131, v11
	s_nop 1
	v_mov_b32_dpp v44, v42 quad_perm:[1,0,3,2] row_mask:0xf bank_mask:0xf
	v_fmac_f32_e32 v44, v131, v11
	s_nop 1
	v_mov_b32_dpp v45, v44 quad_perm:[2,3,0,1] row_mask:0xf bank_mask:0xf
	s_and_saveexec_b64 s[0:1], vcc
	s_cbranch_execz .LBB0_469
	v_add_f32_e32 v44, v44, v45
	ds_write_b32 v15, v44 offset:140
.LBB0_469:
	s_or_b64 exec, exec, s[0:1]
	v_mul_f32_e32 v44, v130, v11
	s_nop 1
	v_mov_b32_dpp v45, v44 quad_perm:[1,0,3,2] row_mask:0xf bank_mask:0xf
	v_fmac_f32_e32 v45, v130, v11
	s_nop 1
	v_mov_b32_dpp v46, v45 quad_perm:[2,3,0,1] row_mask:0xf bank_mask:0xf
	s_and_saveexec_b64 s[0:1], vcc
	s_cbranch_execz .LBB0_471
	v_add_f32_e32 v45, v45, v46
	ds_write_b32 v15, v45 offset:144
.LBB0_471:
	s_or_b64 exec, exec, s[0:1]
	v_mul_f32_e32 v45, v129, v11
	s_nop 1
	v_mov_b32_dpp v46, v45 quad_perm:[1,0,3,2] row_mask:0xf bank_mask:0xf
	v_fmac_f32_e32 v46, v129, v11
	s_nop 1
	v_mov_b32_dpp v47, v46 quad_perm:[2,3,0,1] row_mask:0xf bank_mask:0xf
	s_and_saveexec_b64 s[0:1], vcc
	s_cbranch_execz .LBB0_473
	v_add_f32_e32 v46, v46, v47
	ds_write_b32 v15, v46 offset:148
.LBB0_473:
	s_or_b64 exec, exec, s[0:1]
	v_mul_f32_e32 v46, v128, v11
	s_nop 1
	v_mov_b32_dpp v47, v46 quad_perm:[1,0,3,2] row_mask:0xf bank_mask:0xf
	v_fmac_f32_e32 v47, v128, v11
	s_nop 1
	v_mov_b32_dpp v48, v47 quad_perm:[2,3,0,1] row_mask:0xf bank_mask:0xf
	s_and_saveexec_b64 s[0:1], vcc
	s_cbranch_execz .LBB0_475
	v_add_f32_e32 v47, v47, v48
	ds_write_b32 v15, v47 offset:152
.LBB0_475:
	s_or_b64 exec, exec, s[0:1]
	v_mul_f32_e32 v48, v124, v11
	s_nop 1
	v_mov_b32_dpp v47, v48 quad_perm:[1,0,3,2] row_mask:0xf bank_mask:0xf
	v_fmac_f32_e32 v47, v124, v11
	s_nop 1
	v_mov_b32_dpp v49, v47 quad_perm:[2,3,0,1] row_mask:0xf bank_mask:0xf
	s_and_saveexec_b64 s[0:1], vcc
	s_cbranch_execz .LBB0_477
	v_add_f32_e32 v47, v47, v49
	ds_write_b32 v15, v47 offset:156
.LBB0_477:
	s_or_b64 exec, exec, s[0:1]
	v_mul_f32_e32 v47, v65, v11
	s_nop 1
	v_mov_b32_dpp v49, v47 quad_perm:[1,0,3,2] row_mask:0xf bank_mask:0xf
	v_fmac_f32_e32 v49, v65, v11
	s_nop 1
	v_mov_b32_dpp v50, v49 quad_perm:[2,3,0,1] row_mask:0xf bank_mask:0xf
	s_and_saveexec_b64 s[0:1], vcc
	s_cbranch_execz .LBB0_479
	v_add_f32_e32 v49, v49, v50
	ds_write_b32 v15, v49 offset:256
.LBB0_479:
	s_or_b64 exec, exec, s[0:1]
	v_mul_f32_e32 v49, v62, v11
	s_nop 1
	v_mov_b32_dpp v50, v49 quad_perm:[1,0,3,2] row_mask:0xf bank_mask:0xf
	v_fmac_f32_e32 v50, v62, v11
	s_nop 1
	v_mov_b32_dpp v51, v50 quad_perm:[2,3,0,1] row_mask:0xf bank_mask:0xf
	s_and_saveexec_b64 s[0:1], vcc
	s_cbranch_execz .LBB0_481
	v_add_f32_e32 v50, v50, v51
	ds_write_b32 v15, v50 offset:260
.LBB0_481:
	s_or_b64 exec, exec, s[0:1]
	v_mul_f32_e32 v50, v126, v11
	s_nop 1
	v_mov_b32_dpp v51, v50 quad_perm:[1,0,3,2] row_mask:0xf bank_mask:0xf
	v_fmac_f32_e32 v51, v126, v11
	s_nop 1
	v_mov_b32_dpp v62, v51 quad_perm:[2,3,0,1] row_mask:0xf bank_mask:0xf
	s_and_saveexec_b64 s[0:1], vcc
	s_cbranch_execz .LBB0_483
	v_add_f32_e32 v51, v51, v62
	ds_write_b32 v15, v51 offset:264
.LBB0_483:
	s_or_b64 exec, exec, s[0:1]
	v_mul_f32_e32 v51, v71, v11
	s_nop 1
	v_mov_b32_dpp v62, v51 quad_perm:[1,0,3,2] row_mask:0xf bank_mask:0xf
	v_fmac_f32_e32 v62, v71, v11
	s_nop 1
	v_mov_b32_dpp v65, v62 quad_perm:[2,3,0,1] row_mask:0xf bank_mask:0xf
	s_and_saveexec_b64 s[0:1], vcc
	s_cbranch_execz .LBB0_485
	v_add_f32_e32 v62, v62, v65
	ds_write_b32 v15, v62 offset:268
.LBB0_485:
	s_or_b64 exec, exec, s[0:1]
	v_mul_f32_e32 v62, v67, v11
	s_nop 1
	v_mov_b32_dpp v65, v62 quad_perm:[1,0,3,2] row_mask:0xf bank_mask:0xf
	v_fmac_f32_e32 v65, v67, v11
	s_nop 1
	v_mov_b32_dpp v67, v65 quad_perm:[2,3,0,1] row_mask:0xf bank_mask:0xf
	s_and_saveexec_b64 s[0:1], vcc
	s_cbranch_execz .LBB0_487
	v_add_f32_e32 v65, v65, v67
	ds_write_b32 v15, v65 offset:272
.LBB0_487:
	s_or_b64 exec, exec, s[0:1]
	v_mul_f32_e32 v65, v127, v11
	s_nop 1
	v_mov_b32_dpp v67, v65 quad_perm:[1,0,3,2] row_mask:0xf bank_mask:0xf
	v_fmac_f32_e32 v67, v127, v11
	s_nop 1
	v_mov_b32_dpp v71, v67 quad_perm:[2,3,0,1] row_mask:0xf bank_mask:0xf
	s_and_saveexec_b64 s[0:1], vcc
	s_cbranch_execz .LBB0_489
	v_add_f32_e32 v67, v67, v71
	ds_write_b32 v15, v67 offset:276
.LBB0_489:
	s_or_b64 exec, exec, s[0:1]
	v_mul_f32_e32 v67, v125, v11
	s_nop 1
	v_mov_b32_dpp v71, v67 quad_perm:[1,0,3,2] row_mask:0xf bank_mask:0xf
	v_fmac_f32_e32 v71, v125, v11
	s_nop 1
	v_mov_b32_dpp v118, v71 quad_perm:[2,3,0,1] row_mask:0xf bank_mask:0xf
	s_and_saveexec_b64 s[0:1], vcc
	s_cbranch_execz .LBB0_491
	v_add_f32_e32 v71, v71, v118
	ds_write_b32 v15, v71 offset:280
.LBB0_491:
	s_or_b64 exec, exec, s[0:1]
	v_mul_f32_e32 v71, v70, v11
	s_nop 1
	v_mov_b32_dpp v118, v71 quad_perm:[1,0,3,2] row_mask:0xf bank_mask:0xf
	v_fmac_f32_e32 v118, v70, v11
	s_nop 1
	v_mov_b32_dpp v70, v118 quad_perm:[2,3,0,1] row_mask:0xf bank_mask:0xf
	s_and_saveexec_b64 s[0:1], vcc
	s_cbranch_execz .LBB0_493
	v_add_f32_e32 v70, v118, v70
	ds_write_b32 v15, v70 offset:284
.LBB0_493:
	s_or_b64 exec, exec, s[0:1]
	v_mul_f32_e32 v70, v123, v11
	s_nop 1
	v_mov_b32_dpp v118, v70 quad_perm:[1,0,3,2] row_mask:0xf bank_mask:0xf
	v_fmac_f32_e32 v118, v123, v11
	s_nop 1
	v_mov_b32_dpp v123, v118 quad_perm:[2,3,0,1] row_mask:0xf bank_mask:0xf
	s_and_saveexec_b64 s[0:1], vcc
	s_cbranch_execz .LBB0_495
	v_add_f32_e32 v118, v118, v123
	ds_write_b32 v15, v118 offset:384
.LBB0_495:
	s_or_b64 exec, exec, s[0:1]
	v_mul_f32_e32 v118, v122, v11
	s_nop 1
	v_mov_b32_dpp v123, v118 quad_perm:[1,0,3,2] row_mask:0xf bank_mask:0xf
	v_fmac_f32_e32 v123, v122, v11
	s_nop 1
	v_mov_b32_dpp v122, v123 quad_perm:[2,3,0,1] row_mask:0xf bank_mask:0xf
	s_and_saveexec_b64 s[0:1], vcc
	s_cbranch_execz .LBB0_497
	v_add_f32_e32 v122, v123, v122
	ds_write_b32 v15, v122 offset:388
.LBB0_497:
	s_or_b64 exec, exec, s[0:1]
	v_mul_f32_e32 v122, v121, v11
	s_nop 1
	v_mov_b32_dpp v123, v122 quad_perm:[1,0,3,2] row_mask:0xf bank_mask:0xf
	v_fmac_f32_e32 v123, v121, v11
	s_nop 1
	v_mov_b32_dpp v121, v123 quad_perm:[2,3,0,1] row_mask:0xf bank_mask:0xf
	s_and_saveexec_b64 s[0:1], vcc
	s_cbranch_execz .LBB0_499
	v_add_f32_e32 v121, v123, v121
	ds_write_b32 v15, v121 offset:392
.LBB0_499:
	s_or_b64 exec, exec, s[0:1]
	v_mul_f32_e32 v121, v120, v11
	s_nop 1
	v_mov_b32_dpp v123, v121 quad_perm:[1,0,3,2] row_mask:0xf bank_mask:0xf
	v_fmac_f32_e32 v123, v120, v11
	s_nop 1
	v_mov_b32_dpp v120, v123 quad_perm:[2,3,0,1] row_mask:0xf bank_mask:0xf
	s_and_saveexec_b64 s[0:1], vcc
	s_cbranch_execz .LBB0_501
	v_add_f32_e32 v120, v123, v120
	ds_write_b32 v15, v120 offset:396
.LBB0_501:
	s_or_b64 exec, exec, s[0:1]
	v_mul_f32_e32 v120, v119, v11
	s_nop 1
	v_mov_b32_dpp v123, v120 quad_perm:[1,0,3,2] row_mask:0xf bank_mask:0xf
	v_fmac_f32_e32 v123, v119, v11
	s_nop 1
	v_mov_b32_dpp v119, v123 quad_perm:[2,3,0,1] row_mask:0xf bank_mask:0xf
	s_and_saveexec_b64 s[0:1], vcc
	s_cbranch_execz .LBB0_503
	v_add_f32_e32 v119, v123, v119
	ds_write_b32 v15, v119 offset:400
.LBB0_503:
	s_or_b64 exec, exec, s[0:1]
	v_mul_f32_e32 v119, v69, v11
	s_nop 1
	v_mov_b32_dpp v123, v119 quad_perm:[1,0,3,2] row_mask:0xf bank_mask:0xf
	v_fmac_f32_e32 v123, v69, v11
	s_nop 1
	v_mov_b32_dpp v69, v123 quad_perm:[2,3,0,1] row_mask:0xf bank_mask:0xf
	s_and_saveexec_b64 s[0:1], vcc
	s_cbranch_execz .LBB0_505
	v_add_f32_e32 v69, v123, v69
	ds_write_b32 v15, v69 offset:404
.LBB0_505:
	s_or_b64 exec, exec, s[0:1]
	v_mul_f32_e32 v69, v68, v11
	s_nop 1
	v_mov_b32_dpp v123, v69 quad_perm:[1,0,3,2] row_mask:0xf bank_mask:0xf
	v_fmac_f32_e32 v123, v68, v11
	s_nop 1
	v_mov_b32_dpp v68, v123 quad_perm:[2,3,0,1] row_mask:0xf bank_mask:0xf
	s_and_saveexec_b64 s[0:1], vcc
	s_cbranch_execz .LBB0_507
	v_add_f32_e32 v68, v123, v68
	ds_write_b32 v15, v68 offset:408
.LBB0_507:
	s_or_b64 exec, exec, s[0:1]
	v_mul_f32_e32 v68, v66, v11
	s_nop 1
	v_mov_b32_dpp v123, v68 quad_perm:[1,0,3,2] row_mask:0xf bank_mask:0xf
	v_fmac_f32_e32 v123, v66, v11
	s_nop 1
	v_mov_b32_dpp v66, v123 quad_perm:[2,3,0,1] row_mask:0xf bank_mask:0xf
	s_and_saveexec_b64 s[0:1], vcc
	s_cbranch_execz .LBB0_509
	v_add_f32_e32 v66, v123, v66
	ds_write_b32 v15, v66 offset:412
.LBB0_509:
	s_or_b64 exec, exec, s[0:1]
	v_mul_f32_e32 v66, v64, v11
	s_nop 1
	v_mov_b32_dpp v123, v66 quad_perm:[1,0,3,2] row_mask:0xf bank_mask:0xf
	v_fmac_f32_e32 v123, v64, v11
	s_nop 1
	v_mov_b32_dpp v64, v123 quad_perm:[2,3,0,1] row_mask:0xf bank_mask:0xf
	s_and_saveexec_b64 s[0:1], vcc
	s_cbranch_execz .LBB0_511
	v_add_f32_e32 v64, v123, v64
	ds_write_b32 v15, v64 offset:512
.LBB0_511:
	s_or_b64 exec, exec, s[0:1]
	v_mul_f32_e32 v64, v63, v11
	s_nop 1
	v_mov_b32_dpp v123, v64 quad_perm:[1,0,3,2] row_mask:0xf bank_mask:0xf
	v_fmac_f32_e32 v123, v63, v11
	s_nop 1
	v_mov_b32_dpp v63, v123 quad_perm:[2,3,0,1] row_mask:0xf bank_mask:0xf
	s_and_saveexec_b64 s[0:1], vcc
	s_cbranch_execz .LBB0_513
	v_add_f32_e32 v63, v123, v63
	ds_write_b32 v15, v63 offset:516
.LBB0_513:
	s_or_b64 exec, exec, s[0:1]
	v_mul_f32_e32 v63, v61, v11
	s_nop 1
	v_mov_b32_dpp v123, v63 quad_perm:[1,0,3,2] row_mask:0xf bank_mask:0xf
	v_fmac_f32_e32 v123, v61, v11
	s_nop 1
	v_mov_b32_dpp v61, v123 quad_perm:[2,3,0,1] row_mask:0xf bank_mask:0xf
	s_and_saveexec_b64 s[0:1], vcc
	s_cbranch_execz .LBB0_515
	v_add_f32_e32 v61, v123, v61
	ds_write_b32 v15, v61 offset:520
.LBB0_515:
	s_or_b64 exec, exec, s[0:1]
	v_mul_f32_e32 v61, v60, v11
	s_nop 1
	v_mov_b32_dpp v123, v61 quad_perm:[1,0,3,2] row_mask:0xf bank_mask:0xf
	v_fmac_f32_e32 v123, v60, v11
	s_nop 1
	v_mov_b32_dpp v60, v123 quad_perm:[2,3,0,1] row_mask:0xf bank_mask:0xf
	s_and_saveexec_b64 s[0:1], vcc
	s_cbranch_execz .LBB0_517
	v_add_f32_e32 v60, v123, v60
	ds_write_b32 v15, v60 offset:524
.LBB0_517:
	s_or_b64 exec, exec, s[0:1]
	v_mul_f32_e32 v60, v59, v11
	s_nop 1
	v_mov_b32_dpp v123, v60 quad_perm:[1,0,3,2] row_mask:0xf bank_mask:0xf
	v_fmac_f32_e32 v123, v59, v11
	s_nop 1
	v_mov_b32_dpp v59, v123 quad_perm:[2,3,0,1] row_mask:0xf bank_mask:0xf
	s_and_saveexec_b64 s[0:1], vcc
	s_cbranch_execz .LBB0_519
	v_add_f32_e32 v59, v123, v59
	ds_write_b32 v15, v59 offset:528
.LBB0_519:
	s_or_b64 exec, exec, s[0:1]
	v_mul_f32_e32 v59, v58, v11
	s_nop 1
	v_mov_b32_dpp v123, v59 quad_perm:[1,0,3,2] row_mask:0xf bank_mask:0xf
	v_fmac_f32_e32 v123, v58, v11
	s_nop 1
	v_mov_b32_dpp v58, v123 quad_perm:[2,3,0,1] row_mask:0xf bank_mask:0xf
	s_and_saveexec_b64 s[0:1], vcc
	s_cbranch_execz .LBB0_521
	v_add_f32_e32 v58, v123, v58
	ds_write_b32 v15, v58 offset:532
.LBB0_521:
	s_or_b64 exec, exec, s[0:1]
	v_mul_f32_e32 v58, v57, v11
	s_nop 1
	v_mov_b32_dpp v123, v58 quad_perm:[1,0,3,2] row_mask:0xf bank_mask:0xf
	v_fmac_f32_e32 v123, v57, v11
	s_nop 1
	v_mov_b32_dpp v57, v123 quad_perm:[2,3,0,1] row_mask:0xf bank_mask:0xf
	s_and_saveexec_b64 s[0:1], vcc
	s_cbranch_execz .LBB0_523
	v_add_f32_e32 v57, v123, v57
	ds_write_b32 v15, v57 offset:536
.LBB0_523:
	s_or_b64 exec, exec, s[0:1]
	v_mul_f32_e32 v57, v56, v11
	s_nop 1
	v_mov_b32_dpp v123, v57 quad_perm:[1,0,3,2] row_mask:0xf bank_mask:0xf
	v_fmac_f32_e32 v123, v56, v11
	s_nop 1
	v_mov_b32_dpp v56, v123 quad_perm:[2,3,0,1] row_mask:0xf bank_mask:0xf
	s_and_saveexec_b64 s[0:1], vcc
	s_cbranch_execz .LBB0_525
	v_add_f32_e32 v56, v123, v56
	ds_write_b32 v15, v56 offset:540
.LBB0_525:
	s_or_b64 exec, exec, s[0:1]
	v_mul_f32_e32 v56, v55, v11
	s_nop 1
	v_mov_b32_dpp v123, v56 quad_perm:[1,0,3,2] row_mask:0xf bank_mask:0xf
	v_fmac_f32_e32 v123, v55, v11
	s_nop 1
	v_mov_b32_dpp v55, v123 quad_perm:[2,3,0,1] row_mask:0xf bank_mask:0xf
	s_and_saveexec_b64 s[0:1], vcc
	s_cbranch_execz .LBB0_527
	v_add_f32_e32 v55, v123, v55
	ds_write_b32 v15, v55 offset:640
.LBB0_527:
	s_or_b64 exec, exec, s[0:1]
	v_mul_f32_e32 v55, v54, v11
	s_nop 1
	v_mov_b32_dpp v123, v55 quad_perm:[1,0,3,2] row_mask:0xf bank_mask:0xf
	v_fmac_f32_e32 v123, v54, v11
	s_nop 1
	v_mov_b32_dpp v54, v123 quad_perm:[2,3,0,1] row_mask:0xf bank_mask:0xf
	s_and_saveexec_b64 s[0:1], vcc
	s_cbranch_execz .LBB0_529
	v_add_f32_e32 v54, v123, v54
	ds_write_b32 v15, v54 offset:644
.LBB0_529:
	s_or_b64 exec, exec, s[0:1]
	v_mul_f32_e32 v54, v53, v11
	s_nop 1
	v_mov_b32_dpp v123, v54 quad_perm:[1,0,3,2] row_mask:0xf bank_mask:0xf
	v_fmac_f32_e32 v123, v53, v11
	s_nop 1
	v_mov_b32_dpp v53, v123 quad_perm:[2,3,0,1] row_mask:0xf bank_mask:0xf
	s_and_saveexec_b64 s[0:1], vcc
	s_cbranch_execz .LBB0_531
	v_add_f32_e32 v53, v123, v53
	ds_write_b32 v15, v53 offset:648
.LBB0_531:
	s_or_b64 exec, exec, s[0:1]
	v_mul_f32_e32 v53, v52, v11
	s_nop 1
	v_mov_b32_dpp v123, v53 quad_perm:[1,0,3,2] row_mask:0xf bank_mask:0xf
	v_fmac_f32_e32 v123, v52, v11
	s_nop 1
	v_mov_b32_dpp v52, v123 quad_perm:[2,3,0,1] row_mask:0xf bank_mask:0xf
	s_and_saveexec_b64 s[0:1], vcc
	s_cbranch_execz .LBB0_533
	v_add_f32_e32 v52, v123, v52
	ds_write_b32 v15, v52 offset:652
.LBB0_533:
	s_or_b64 exec, exec, s[0:1]
	v_mul_f32_e32 v52, v43, v11
	s_nop 1
	v_mov_b32_dpp v123, v52 quad_perm:[1,0,3,2] row_mask:0xf bank_mask:0xf
	v_fmac_f32_e32 v123, v43, v11
	s_nop 1
	v_mov_b32_dpp v43, v123 quad_perm:[2,3,0,1] row_mask:0xf bank_mask:0xf
	s_and_saveexec_b64 s[0:1], vcc
	s_cbranch_execz .LBB0_535
	v_add_f32_e32 v43, v123, v43
	ds_write_b32 v15, v43 offset:656
.LBB0_535:
	s_or_b64 exec, exec, s[0:1]
	v_mul_f32_e32 v43, v41, v11
	s_nop 1
	v_mov_b32_dpp v123, v43 quad_perm:[1,0,3,2] row_mask:0xf bank_mask:0xf
	v_fmac_f32_e32 v123, v41, v11
	s_nop 1
	v_mov_b32_dpp v41, v123 quad_perm:[2,3,0,1] row_mask:0xf bank_mask:0xf
	s_and_saveexec_b64 s[0:1], vcc
	s_cbranch_execz .LBB0_537
	v_add_f32_e32 v41, v123, v41
	ds_write_b32 v15, v41 offset:660
.LBB0_537:
	s_or_b64 exec, exec, s[0:1]
	v_mul_f32_e32 v41, v40, v11
	s_nop 1
	v_mov_b32_dpp v123, v41 quad_perm:[1,0,3,2] row_mask:0xf bank_mask:0xf
	v_fmac_f32_e32 v123, v40, v11
	s_nop 1
	v_mov_b32_dpp v40, v123 quad_perm:[2,3,0,1] row_mask:0xf bank_mask:0xf
	s_and_saveexec_b64 s[0:1], vcc
	s_cbranch_execz .LBB0_539
	v_add_f32_e32 v40, v123, v40
	ds_write_b32 v15, v40 offset:664
.LBB0_539:
	s_or_b64 exec, exec, s[0:1]
	v_mul_f32_e32 v124, v39, v11
	s_nop 1
	v_mov_b32_dpp v40, v124 quad_perm:[1,0,3,2] row_mask:0xf bank_mask:0xf
	v_fmac_f32_e32 v40, v39, v11
	s_nop 1
	v_mov_b32_dpp v39, v40 quad_perm:[2,3,0,1] row_mask:0xf bank_mask:0xf
	s_and_saveexec_b64 s[0:1], vcc
	s_cbranch_execz .LBB0_541
	v_add_f32_e32 v39, v40, v39
	ds_write_b32 v15, v39 offset:668
.LBB0_541:
	s_or_b64 exec, exec, s[0:1]
	v_mul_f32_e32 v40, v38, v11
	s_nop 1
	v_mov_b32_dpp v39, v40 quad_perm:[1,0,3,2] row_mask:0xf bank_mask:0xf
	v_fmac_f32_e32 v39, v38, v11
	s_nop 1
	v_mov_b32_dpp v38, v39 quad_perm:[2,3,0,1] row_mask:0xf bank_mask:0xf
	s_and_saveexec_b64 s[0:1], vcc
	s_cbranch_execz .LBB0_543
	v_add_f32_e32 v38, v39, v38
	ds_write_b32 v15, v38 offset:768
.LBB0_543:
	s_or_b64 exec, exec, s[0:1]
	v_mul_f32_e32 v123, v30, v11
	s_nop 1
	v_mov_b32_dpp v38, v123 quad_perm:[1,0,3,2] row_mask:0xf bank_mask:0xf
	v_fmac_f32_e32 v38, v30, v11
	s_nop 1
	v_mov_b32_dpp v30, v38 quad_perm:[2,3,0,1] row_mask:0xf bank_mask:0xf
	s_and_saveexec_b64 s[0:1], vcc
	s_cbranch_execz .LBB0_545
	v_add_f32_e32 v30, v38, v30
	ds_write_b32 v15, v30 offset:772
.LBB0_545:
	s_or_b64 exec, exec, s[0:1]
	v_mul_f32_e32 v125, v29, v11
	s_nop 1
	v_mov_b32_dpp v30, v125 quad_perm:[1,0,3,2] row_mask:0xf bank_mask:0xf
	v_fmac_f32_e32 v30, v29, v11
	s_nop 1
	v_mov_b32_dpp v29, v30 quad_perm:[2,3,0,1] row_mask:0xf bank_mask:0xf
	s_and_saveexec_b64 s[0:1], vcc
	s_cbranch_execz .LBB0_547
	v_add_f32_e32 v29, v30, v29
	ds_write_b32 v15, v29 offset:776
.LBB0_547:
	s_or_b64 exec, exec, s[0:1]
	v_mul_f32_e32 v126, v27, v11
	s_nop 1
	v_mov_b32_dpp v29, v126 quad_perm:[1,0,3,2] row_mask:0xf bank_mask:0xf
	v_fmac_f32_e32 v29, v27, v11
	s_nop 1
	v_mov_b32_dpp v27, v29 quad_perm:[2,3,0,1] row_mask:0xf bank_mask:0xf
	s_and_saveexec_b64 s[0:1], vcc
	s_cbranch_execz .LBB0_549
	v_add_f32_e32 v27, v29, v27
	ds_write_b32 v15, v27 offset:780
.LBB0_549:
	s_or_b64 exec, exec, s[0:1]
	v_mul_f32_e32 v127, v26, v11
	s_nop 1
	v_mov_b32_dpp v27, v127 quad_perm:[1,0,3,2] row_mask:0xf bank_mask:0xf
	v_fmac_f32_e32 v27, v26, v11
	s_nop 1
	v_mov_b32_dpp v26, v27 quad_perm:[2,3,0,1] row_mask:0xf bank_mask:0xf
	s_and_saveexec_b64 s[0:1], vcc
	s_cbranch_execz .LBB0_551
	v_add_f32_e32 v26, v27, v26
	ds_write_b32 v15, v26 offset:784
.LBB0_551:
	s_or_b64 exec, exec, s[0:1]
	v_mul_f32_e32 v128, v24, v11
	s_nop 1
	v_mov_b32_dpp v26, v128 quad_perm:[1,0,3,2] row_mask:0xf bank_mask:0xf
	v_fmac_f32_e32 v26, v24, v11
	s_nop 1
	v_mov_b32_dpp v24, v26 quad_perm:[2,3,0,1] row_mask:0xf bank_mask:0xf
	s_and_saveexec_b64 s[0:1], vcc
	s_cbranch_execz .LBB0_553
	v_add_f32_e32 v24, v26, v24
	ds_write_b32 v15, v24 offset:788
.LBB0_553:
	s_or_b64 exec, exec, s[0:1]
	v_mul_f32_e32 v129, v22, v11
	s_nop 1
	v_mov_b32_dpp v24, v129 quad_perm:[1,0,3,2] row_mask:0xf bank_mask:0xf
	v_fmac_f32_e32 v24, v22, v11
	s_nop 1
	v_mov_b32_dpp v22, v24 quad_perm:[2,3,0,1] row_mask:0xf bank_mask:0xf
	s_and_saveexec_b64 s[0:1], vcc
	s_cbranch_execz .LBB0_555
	v_add_f32_e32 v22, v24, v22
	ds_write_b32 v15, v22 offset:792
.LBB0_555:
	s_or_b64 exec, exec, s[0:1]
	v_mul_f32_e32 v131, v21, v11
	s_nop 1
	v_mov_b32_dpp v22, v131 quad_perm:[1,0,3,2] row_mask:0xf bank_mask:0xf
	v_fmac_f32_e32 v22, v21, v11
	s_nop 1
	v_mov_b32_dpp v21, v22 quad_perm:[2,3,0,1] row_mask:0xf bank_mask:0xf
	s_and_saveexec_b64 s[0:1], vcc
	s_cbranch_execz .LBB0_557
	v_add_f32_e32 v21, v22, v21
	ds_write_b32 v15, v21 offset:796
.LBB0_557:
	s_or_b64 exec, exec, s[0:1]
	v_mul_f32_e32 v130, v20, v11
	s_nop 1
	v_mov_b32_dpp v21, v130 quad_perm:[1,0,3,2] row_mask:0xf bank_mask:0xf
	v_fmac_f32_e32 v21, v20, v11
	s_nop 1
	v_mov_b32_dpp v20, v21 quad_perm:[2,3,0,1] row_mask:0xf bank_mask:0xf
	s_and_saveexec_b64 s[0:1], vcc
	s_cbranch_execz .LBB0_559
	v_add_f32_e32 v20, v21, v20
	ds_write_b32 v15, v20 offset:896
.LBB0_559:
	s_or_b64 exec, exec, s[0:1]
	v_mul_f32_e32 v132, v19, v11
	s_nop 1
	v_mov_b32_dpp v20, v132 quad_perm:[1,0,3,2] row_mask:0xf bank_mask:0xf
	v_fmac_f32_e32 v20, v19, v11
	s_nop 1
	v_mov_b32_dpp v19, v20 quad_perm:[2,3,0,1] row_mask:0xf bank_mask:0xf
	s_and_saveexec_b64 s[0:1], vcc
	s_cbranch_execz .LBB0_561
	v_add_f32_e32 v19, v20, v19
	ds_write_b32 v15, v19 offset:900
.LBB0_561:
	s_or_b64 exec, exec, s[0:1]
	v_mul_f32_e32 v133, v17, v11
	s_nop 1
	v_mov_b32_dpp v19, v133 quad_perm:[1,0,3,2] row_mask:0xf bank_mask:0xf
	v_fmac_f32_e32 v19, v17, v11
	s_nop 1
	v_mov_b32_dpp v17, v19 quad_perm:[2,3,0,1] row_mask:0xf bank_mask:0xf
	s_and_saveexec_b64 s[0:1], vcc
	s_cbranch_execz .LBB0_563
	v_add_f32_e32 v17, v19, v17
	ds_write_b32 v15, v17 offset:904
.LBB0_563:
	s_or_b64 exec, exec, s[0:1]
	v_mul_f32_e32 v134, v14, v11
	s_nop 1
	v_mov_b32_dpp v17, v134 quad_perm:[1,0,3,2] row_mask:0xf bank_mask:0xf
	v_fmac_f32_e32 v17, v14, v11
	s_nop 1
	v_mov_b32_dpp v14, v17 quad_perm:[2,3,0,1] row_mask:0xf bank_mask:0xf
	s_and_saveexec_b64 s[0:1], vcc
	s_cbranch_execz .LBB0_565
	v_add_f32_e32 v14, v17, v14
	ds_write_b32 v15, v14 offset:908
.LBB0_565:
	s_or_b64 exec, exec, s[0:1]
	v_mul_f32_e32 v14, v13, v11
	s_nop 1
	v_mov_b32_dpp v17, v14 quad_perm:[1,0,3,2] row_mask:0xf bank_mask:0xf
	v_fmac_f32_e32 v17, v13, v11
	s_nop 1
	v_mov_b32_dpp v13, v17 quad_perm:[2,3,0,1] row_mask:0xf bank_mask:0xf
	s_and_saveexec_b64 s[0:1], vcc
	s_cbranch_execz .LBB0_567
	v_add_f32_e32 v13, v17, v13
	ds_write_b32 v15, v13 offset:912
.LBB0_567:
	s_or_b64 exec, exec, s[0:1]
	v_mul_f32_e32 v13, v12, v11
	s_nop 1
	v_mov_b32_dpp v17, v13 quad_perm:[1,0,3,2] row_mask:0xf bank_mask:0xf
	v_fmac_f32_e32 v17, v12, v11
	s_nop 1
	v_mov_b32_dpp v12, v17 quad_perm:[2,3,0,1] row_mask:0xf bank_mask:0xf
	s_and_saveexec_b64 s[0:1], vcc
	s_cbranch_execz .LBB0_569
	v_add_f32_e32 v12, v17, v12
	ds_write_b32 v15, v12 offset:916
.LBB0_569:
	s_or_b64 exec, exec, s[0:1]
	v_mul_f32_e32 v12, v9, v11
	s_nop 1
	v_mov_b32_dpp v17, v12 quad_perm:[1,0,3,2] row_mask:0xf bank_mask:0xf
	v_fmac_f32_e32 v17, v9, v11
	s_nop 1
	v_mov_b32_dpp v9, v17 quad_perm:[2,3,0,1] row_mask:0xf bank_mask:0xf
	s_and_saveexec_b64 s[0:1], vcc
	s_cbranch_execz .LBB0_571
	v_add_f32_e32 v9, v17, v9
	ds_write_b32 v15, v9 offset:920
.LBB0_571:
	s_or_b64 exec, exec, s[0:1]
	v_mul_f32_e32 v9, v8, v11
	s_nop 1
	v_mov_b32_dpp v17, v9 quad_perm:[1,0,3,2] row_mask:0xf bank_mask:0xf
	v_fmac_f32_e32 v17, v8, v11
	s_nop 1
	v_mov_b32_dpp v8, v17 quad_perm:[2,3,0,1] row_mask:0xf bank_mask:0xf
	s_and_saveexec_b64 s[0:1], vcc
	s_cbranch_execz .LBB0_573
	v_add_f32_e32 v8, v17, v8
	ds_write_b32 v15, v8 offset:924

.LBB0_602:
	s_mov_b32 s0, 0xffff
	v_cmp_ne_u32_e32 vcc, s0, v127
	s_and_b64 s[0:1], s[6:7], vcc
	v_cndmask_b32_e64 v40, 0, 1, s[0:1]
	s_mul_i32 s0, s63, 0x2500
	s_add_i32 s0, s0, 0
	v_cmp_ne_u32_e32 vcc, 0, v40
	v_add_u32_e32 v40, s0, v110
	v_add_u32_e32 v41, s0, v111
	v_add_u32_e32 v42, s0, v112
	v_add_u32_e32 v43, s0, v113
	s_mul_i32 s0, s63, 0x2400
	v_add3_u32 v126, v40, v79, v103
	v_add3_u32 v125, v41, v79, v103
	v_add3_u32 v124, v42, v104, v103
	v_add3_u32 v90, v43, v104, v103
	v_add_u32_e32 v123, s0, v115
	s_cbranch_vccz .LBB0_604
	ds_read_b128 v[40:43], v126
	ds_read_b128 v[44:47], v126 offset:64
	v_add_u32_e32 v146, v123, v120
	s_waitcnt lgkmcnt(1)
	v_mfma_f32_16x16x32_bf16 v[40:43], v[40:43], v[4:7], 0
	ds_read_b128 v[128:131], v90 offset:64
	s_waitcnt lgkmcnt(1)
	v_mfma_f32_16x16x32_bf16 v[52:55], v[44:47], v[0:3], v[40:43]
	ds_read_b128 v[44:47], v125 offset:64
	s_nop 3
	ds_read_b128 v[40:43], v125
	s_waitcnt lgkmcnt(0)
	v_mfma_f32_16x16x32_bf16 v[40:43], v[40:43], v[4:7], 0
	v_mfma_f32_16x16x32_bf16 v[48:51], v[44:47], v[0:3], v[40:43]
	ds_read_b128 v[44:47], v124 offset:64
	s_nop 5
	ds_read_b128 v[40:43], v124
	s_waitcnt lgkmcnt(0)
	v_mfma_f32_16x16x32_bf16 v[40:43], v[40:43], v[4:7], 0
	v_mfma_f32_16x16x32_bf16 v[44:47], v[44:47], v[0:3], v[40:43]
	s_nop 6
	ds_read_b128 v[40:43], v90
	s_waitcnt lgkmcnt(0)
	v_mfma_f32_16x16x32_bf16 v[40:43], v[40:43], v[4:7], 0
	v_mfma_f32_16x16x32_bf16 v[40:43], v[128:131], v[0:3], v[40:43]
	v_and_b32_e32 v128, 1, v127
	v_cmp_eq_u32_e32 vcc, 0, v128
	v_max_f32_e32 v128, v52, v52
	v_max_f32_e32 v128, 0xf149f2ca, v128
	v_and_b32_e32 v129, 2, v127
	v_cndmask_b32_e32 v128, v128, v92, vcc
	v_cmp_eq_u32_e64 s[10:11], 0, v129
	v_max_f32_e32 v129, v53, v53
	v_max_f32_e32 v129, v128, v129
	v_cndmask_b32_e64 v128, v129, v128, s[10:11]
	v_and_b32_e32 v129, 4, v127
	v_cmp_eq_u32_e64 s[26:27], 0, v129
	v_max_f32_e32 v129, v54, v54
	v_max_f32_e32 v129, v128, v129
	v_cndmask_b32_e64 v128, v129, v128, s[26:27]
	v_and_b32_e32 v129, 8, v127
	v_cmp_eq_u32_e64 s[30:31], 0, v129
	v_max_f32_e32 v129, v55, v55
	v_max_f32_e32 v129, v128, v129
	v_cndmask_b32_e64 v128, v129, v128, s[30:31]
	v_and_b32_e32 v129, 16, v127
	v_cmp_eq_u32_e64 s[24:25], 0, v129
	v_max_f32_e32 v129, v48, v48
	v_max_f32_e32 v129, v128, v129
	v_cndmask_b32_e64 v128, v129, v128, s[24:25]
	v_and_b32_e32 v129, 32, v127
	v_cmp_eq_u32_e64 s[28:29], 0, v129
	v_max_f32_e32 v129, v128, v128
	v_max_f32_e32 v130, v49, v49
	v_max_f32_e32 v129, v129, v130
	v_cndmask_b32_e64 v128, v129, v128, s[28:29]
	v_and_b32_e32 v129, 64, v127
	v_cmp_eq_u32_e64 s[18:19], 0, v129
	v_max_f32_e32 v129, v128, v128
	v_max_f32_e32 v130, v50, v50
	v_max_f32_e32 v129, v129, v130
	v_cndmask_b32_e64 v128, v129, v128, s[18:19]
	v_and_b32_e32 v129, 0x80, v127
	v_cmp_eq_u32_e64 s[20:21], 0, v129
	v_max_f32_e32 v129, v128, v128
	v_max_f32_e32 v130, v51, v51
	v_max_f32_e32 v129, v129, v130
	v_cndmask_b32_e64 v128, v129, v128, s[20:21]
	v_and_b32_e32 v129, 0x100, v127
	v_cmp_eq_u32_e64 s[22:23], 0, v129
	v_max_f32_e32 v129, v128, v128
	v_max_f32_e32 v130, v44, v44
	v_max_f32_e32 v129, v129, v130
	v_cndmask_b32_e64 v128, v129, v128, s[22:23]
	v_and_b32_e32 v129, 0x200, v127
	v_cmp_eq_u32_e64 s[8:9], 0, v129
	v_max_f32_e32 v129, v128, v128
	v_max_f32_e32 v130, v45, v45
	v_max_f32_e32 v129, v129, v130
	v_cndmask_b32_e64 v128, v129, v128, s[8:9]
	v_and_b32_e32 v129, 0x400, v127
	v_cmp_eq_u32_e64 s[12:13], 0, v129
	v_max_f32_e32 v129, v128, v128
	v_max_f32_e32 v130, v46, v46
	v_max_f32_e32 v129, v129, v130
	v_cndmask_b32_e64 v128, v129, v128, s[12:13]
	v_and_b32_e32 v129, 0x800, v127
	v_cmp_eq_u32_e64 s[14:15], 0, v129
	v_max_f32_e32 v129, v128, v128
	v_max_f32_e32 v130, v47, v47
	v_max_f32_e32 v129, v129, v130
	v_cndmask_b32_e64 v128, v129, v128, s[14:15]
	v_and_b32_e32 v129, 0x1000, v127
	v_cmp_eq_u32_e64 s[16:17], 0, v129
	v_max_f32_e32 v129, v128, v128
	v_max_f32_e32 v130, v40, v40
	v_max_f32_e32 v129, v129, v130
	v_cndmask_b32_e64 v128, v129, v128, s[16:17]
	v_and_b32_e32 v129, 0x2000, v127
	v_cmp_eq_u32_e64 s[0:1], 0, v129
	v_max_f32_e32 v129, v128, v128
	v_max_f32_e32 v130, v41, v41
	v_max_f32_e32 v129, v129, v130
	v_cndmask_b32_e64 v128, v129, v128, s[0:1]
	v_and_b32_e32 v129, 0x4000, v127
	v_cmp_eq_u32_e64 s[2:3], 0, v129
	v_max_f32_e32 v129, v128, v128
	v_max_f32_e32 v130, v42, v42
	v_max_f32_e32 v129, v129, v130
	v_cndmask_b32_e64 v128, v129, v128, s[2:3]
	v_and_b32_e32 v127, 0x8000, v127
	v_cmp_eq_u32_e64 s[4:5], 0, v127
	v_max_f32_e32 v127, v128, v128
	v_max_f32_e32 v129, v43, v43
	v_max_f32_e32 v127, v127, v129
	v_cndmask_b32_e64 v127, v127, v128, s[4:5]
	v_mov_b32_e32 v128, v127
	s_nop 1
	v_permlane16_swap_b32_e32 v128, v127
	v_max_f32_e32 v127, v127, v128
	v_mov_b32_e32 v128, v127
	s_nop 1
	v_permlane32_swap_b32_e32 v128, v127
	v_max3_f32 v127, v122, v127, v128
	v_sub_f32_e32 v53, v53, v127
	v_exp_f32_e32 v53, v53
	v_sub_f32_e32 v49, v49, v127
	v_exp_f32_e32 v49, v49
	v_sub_f32_e32 v52, v52, v127
	v_cndmask_b32_e64 v131, v53, 0, s[10:11]
	v_sub_f32_e32 v53, v54, v127
	v_exp_f32_e32 v53, v53
	v_exp_f32_e32 v52, v52
	v_sub_f32_e32 v45, v45, v127
	v_cndmask_b32_e64 v135, v49, 0, s[28:29]
	v_sub_f32_e32 v49, v50, v127
	v_exp_f32_e32 v45, v45
	v_cndmask_b32_e64 v132, v53, 0, s[26:27]
	v_sub_f32_e32 v53, v55, v127
	v_exp_f32_e32 v49, v49
	v_exp_f32_e32 v53, v53
	v_sub_f32_e32 v48, v48, v127
	v_cndmask_b32_e64 v130, v52, 0, vcc
	v_exp_f32_e32 v48, v48
	v_sub_f32_e32 v41, v41, v127
	v_add_f32_e32 v52, 0, v130
	v_cndmask_b32_e64 v139, v45, 0, s[8:9]
	v_sub_f32_e32 v45, v46, v127
	v_exp_f32_e32 v41, v41
	v_add_f32_e32 v52, v131, v52
	v_cndmask_b32_e64 v136, v49, 0, s[18:19]
	v_sub_f32_e32 v49, v51, v127
	v_exp_f32_e32 v45, v45
	v_add_f32_e32 v52, v132, v52
	v_cndmask_b32_e64 v133, v53, 0, s[30:31]
	v_exp_f32_e32 v49, v49
	v_sub_f32_e32 v44, v44, v127
	v_add_f32_e32 v52, v133, v52
	v_cndmask_b32_e64 v134, v48, 0, s[24:25]
	v_exp_f32_e32 v44, v44
	v_add_f32_e32 v48, v134, v52
	v_cndmask_b32_e64 v143, v41, 0, s[0:1]
	v_sub_f32_e32 v41, v42, v127
	v_sub_f32_e32 v129, v122, v127
	v_add_f32_e32 v48, v135, v48
	v_cndmask_b32_e64 v140, v45, 0, s[12:13]
	v_sub_f32_e32 v45, v47, v127
	v_exp_f32_e32 v41, v41
	v_add_f32_e32 v48, v136, v48
	v_cndmask_b32_e64 v137, v49, 0, s[20:21]
	v_exp_f32_e32 v45, v45
	v_sub_f32_e32 v40, v40, v127
	v_exp_f32_e32 v52, v129
	v_add_u32_e32 v129, v123, v119
	v_add_f32_e32 v48, v137, v48
	v_cndmask_b32_e64 v138, v44, 0, s[22:23]
	v_exp_f32_e32 v40, v40
	v_cvt_pk_bf16_f32 v130, v130, v131
	v_cvt_pk_bf16_f32 v131, v132, v133
	v_cvt_pk_bf16_f32 v132, v134, v135
	v_cvt_pk_bf16_f32 v133, v136, v137
	ds_read_b128 v[134:137], v129 offset:38912
	v_add_f32_e32 v44, v138, v48
	v_add_f32_e32 v44, v139, v44
	v_cndmask_b32_e64 v144, v41, 0, s[2:3]
	v_sub_f32_e32 v41, v43, v127
	v_add_f32_e32 v44, v140, v44
	v_cndmask_b32_e64 v141, v45, 0, s[14:15]
	v_exp_f32_e32 v41, v41
	v_add_f32_e32 v44, v141, v44
	v_cndmask_b32_e64 v142, v40, 0, s[16:17]
	v_add_f32_e32 v40, v142, v44
	v_add_f32_e32 v40, v143, v40
	v_add_f32_e32 v40, v144, v40
	v_cndmask_b32_e64 v145, v41, 0, s[4:5]
	v_add_f32_e32 v128, v145, v40
	v_pk_mul_f32 v[42:43], v[38:39], v[52:53] op_sel_hi:[1,0]
	v_pk_mul_f32 v[40:41], v[36:37], v[52:53] op_sel_hi:[1,0]
	v_pk_mul_f32 v[46:47], v[34:35], v[52:53] op_sel_hi:[1,0]
	v_pk_mul_f32 v[44:45], v[32:33], v[52:53] op_sel_hi:[1,0]
	s_waitcnt lgkmcnt(0)
	v_mfma_f32_16x16x32_bf16 v[40:43], v[134:137], v[130:133], v[40:43]
	ds_read_b128 v[134:137], v129 offset:41216
	v_pk_mul_f32 v[50:51], v[30:31], v[52:53] op_sel_hi:[1,0]
	v_pk_mul_f32 v[48:49], v[28:29], v[52:53] op_sel_hi:[1,0]
	s_waitcnt lgkmcnt(0)
	v_mfma_f32_16x16x32_bf16 v[44:47], v[134:137], v[130:133], v[44:47]
	ds_read_b128 v[134:137], v129 offset:43520
	v_fmac_f32_e32 v128, v121, v52
	v_pk_mul_f32 v[54:55], v[26:27], v[52:53] op_sel_hi:[1,0]
	s_waitcnt lgkmcnt(0)
	v_mfma_f32_16x16x32_bf16 v[48:51], v[134:137], v[130:133], v[48:51]
	ds_read_b128 v[134:137], v146 offset:38912
	v_pk_mul_f32 v[52:53], v[24:25], v[52:53] op_sel_hi:[1,0]
	s_waitcnt lgkmcnt(0)
	s_nop 0
	v_mfma_f32_16x16x32_bf16 v[52:55], v[134:137], v[130:133], v[52:55]
	v_cvt_pk_bf16_f32 v130, v138, v139
	v_cvt_pk_bf16_f32 v131, v140, v141
	v_cvt_pk_bf16_f32 v132, v142, v143
	v_cvt_pk_bf16_f32 v133, v144, v145
	ds_read_b128 v[134:137], v129 offset:38976
	s_waitcnt lgkmcnt(0)
	v_mfma_f32_16x16x32_bf16 v[40:43], v[134:137], v[130:133], v[40:43]
	ds_read_b128 v[134:137], v129 offset:41280
	s_waitcnt lgkmcnt(0)
	v_mfma_f32_16x16x32_bf16 v[44:47], v[134:137], v[130:133], v[44:47]
	ds_read_b128 v[134:137], v129 offset:43584
	s_waitcnt lgkmcnt(0)
	v_mfma_f32_16x16x32_bf16 v[48:51], v[134:137], v[130:133], v[48:51]
	ds_read_b128 v[134:137], v146 offset:38976
	s_waitcnt lgkmcnt(0)
	v_mfma_f32_16x16x32_bf16 v[52:55], v[134:137], v[130:133], v[52:55]
	s_cbranch_execz .LBB0_605
	s_branch .LBB0_608
.LBB0_604:
.LBB0_605:
	ds_read_b128 v[40:43], v126
	ds_read_b128 v[44:47], v126 offset:64
	v_cndmask_b32_e64 v128, v102, 0, s[6:7]
	v_mov_b32_e32 v129, v128
	v_mov_b32_e32 v130, v128
	v_mov_b32_e32 v131, v128
	ds_read_b128 v[48:51], v125
	ds_read_b128 v[132:135], v125 offset:64
	s_waitcnt lgkmcnt(1)
	v_mfma_f32_16x16x32_bf16 v[48:51], v[48:51], v[4:7], v[128:131]
	v_mfma_f32_16x16x32_bf16 v[40:43], v[40:43], v[4:7], v[128:131]
	v_mfma_f32_16x16x32_bf16 v[52:55], v[44:47], v[0:3], v[40:43]
	s_nop 6
	ds_read_b128 v[40:43], v124
	ds_read_b128 v[44:47], v124 offset:64
	v_max_f32_e32 v136, v54, v54
	s_waitcnt lgkmcnt(2)
	v_mfma_f32_16x16x32_bf16 v[48:51], v[132:135], v[0:3], v[48:51]
	ds_read_b128 v[124:127], v90
	ds_read_b128 v[132:135], v90 offset:64
	v_max_f32_e32 v90, v55, v55
	v_max_f32_e32 v90, v136, v90
	s_waitcnt lgkmcnt(3)
	v_mfma_f32_16x16x32_bf16 v[40:43], v[40:43], v[4:7], v[128:131]
	s_nop 1
	v_max_f32_e32 v136, v51, v51
	v_max3_f32 v90, v52, v53, v90
	s_waitcnt lgkmcnt(2)
	v_mfma_f32_16x16x32_bf16 v[44:47], v[44:47], v[0:3], v[40:43]
	s_nop 2
	v_max_f32_e32 v40, v50, v50
	v_max_f32_e32 v40, v40, v136
	v_max3_f32 v136, v48, v49, v40
	s_waitcnt lgkmcnt(1)
	v_mfma_f32_16x16x32_bf16 v[40:43], v[124:127], v[4:7], v[128:131]
	v_max_f32_e32 v124, v45, v45
	v_max_f32_e32 v125, v44, v44
	v_max_f32_e32 v124, v125, v124
	s_waitcnt lgkmcnt(0)
	v_mfma_f32_16x16x32_bf16 v[40:43], v[132:135], v[0:3], v[40:43]
	v_max_f32_e32 v125, v47, v47
	v_max_f32_e32 v126, v46, v46
	v_max_f32_e32 v125, v126, v125
	s_nop 4
	v_max_f32_e32 v126, v43, v43
	v_max_f32_e32 v127, v42, v42
	v_max_f32_e32 v126, v127, v126
	v_max3_f32 v126, v40, v41, v126
	v_max3_f32 v124, v124, v125, v126
	v_max3_f32 v90, v90, v136, v124
	v_mov_b32_e32 v124, v90
	s_nop 1
	v_permlane16_swap_b32_e32 v124, v90
	v_max_f32_e32 v90, v90, v124
	v_mov_b32_e32 v124, v90
	s_nop 1
	v_permlane32_swap_b32_e32 v124, v90
	v_max3_f32 v127, v122, v90, v124
	v_sub_f32_e32 v90, v122, v127
	v_exp_f32_e32 v90, v90
	v_cmp_gt_f32_e32 vcc, v127, v122
	s_cbranch_vccz .LBB0_607
	v_pk_mul_f32 v[38:39], v[38:39], v[90:91] op_sel_hi:[1,0]
	v_pk_mul_f32 v[36:37], v[36:37], v[90:91] op_sel_hi:[1,0]
	v_pk_mul_f32 v[34:35], v[34:35], v[90:91] op_sel_hi:[1,0]
	v_pk_mul_f32 v[32:33], v[32:33], v[90:91] op_sel_hi:[1,0]
	v_pk_mul_f32 v[30:31], v[30:31], v[90:91] op_sel_hi:[1,0]
	v_pk_mul_f32 v[28:29], v[28:29], v[90:91] op_sel_hi:[1,0]
	v_pk_mul_f32 v[26:27], v[26:27], v[90:91] op_sel_hi:[1,0]
	v_pk_mul_f32 v[24:25], v[24:25], v[90:91] op_sel_hi:[1,0]
